# up-projection ConvGLU epilogue rewritten by hand: conv parameters loaded once, packed f32 math, DPP row shifts for the neighbour tokens
# speedup vs baseline: 1.0090x; 1.0090x over previous
; #define G_STAGE(bufoff, gbase, voff) do { _Pragma("unroll") for (int _i = 0; _i < 2; ++_i) \
;         __builtin_amdgcn_global_load_lds((const unsigned*)((const char*)(gbase) + (voff)[_i]), (LAS unsigned*)(lds + (bufoff) + ldsw + _i * 8192), 16, 0, 0); } while (0)
; #define G_LDA(dst, b, h) do { _Pragma("unroll") for (int m = 0; m < 4; ++m) _Pragma("unroll") for (int k = 0; k < 2; ++k) dst[m][k] = *(const LAS bf16x8*)(lds + G_SA(b, h) + aoff + m * 2048 + k * 1024); } while (0)
; #define G_LDB(dst, b, h) do { _Pragma("unroll") for (int n = 0; n < 2; ++n) _Pragma("unroll") for (int k = 0; k < 2; ++k) dst[n][k] = *(const LAS bf16x8*)(lds + G_SB(b, h) + boff + n * 2048 + k * 1024); } while (0)
; #define G_MMA(ai, bj, At, Bt_) do { __builtin_amdgcn_s_setprio(1); _Pragma("unroll") for (int m = 0; m < 4; ++m) _Pragma("unroll") for (int n = 0; n < 2; ++n) _Pragma("unroll") for (int k = 0; k < 2; ++k) \
;         acc[ai][bj][m][n] = __builtin_amdgcn_mfma_f32_16x16x32_bf16(Bt_[n][k], At[m][k], acc[ai][bj][m][n], 0, 0, 0); __builtin_amdgcn_s_setprio(0); } while (0)
; #define G_WAIT_V(n) asm volatile("s_waitcnt vmcnt(" #n ")" ::: "memory")
; #define G_WAIT_L(n) asm volatile("s_waitcnt lgkmcnt(" #n ")" ::: "memory")
; #define G_BAR __builtin_amdgcn_s_barrier()
; #define G_SCHED __builtin_amdgcn_sched_barrier(0)
; template <class Epi, bool PERMROWS = false>
; DI void gemm_phase(LAS unsigned char* lds, const bf16_t* A, int lda, const bf16_t* Bt, int K, const Sched& S, const Epi& E) {
;     ...
;             G_LDB(B0, 0, 0); G_SCHED; G_LDA(At, 0, 0); G_STAGE(G_SA(1, 1), a1 + hstepA, voffA);
;             G_WAIT_L(8); G_BAR; G_WAIT_L(0); G_MMA(0, 0, At, B0); G_BAR; G_SCHED;
;             G_LDB(B1, 0, 1); G_STAGE(G_SB(0, 0), b2, voffB);
;             G_BAR; G_WAIT_L(0); G_MMA(0, 1, At, B1); G_BAR;
;             G_LDA(At, 0, 1); G_STAGE(G_SA(0, 0), a2, voffA);
;             G_BAR; G_WAIT_L(0); G_MMA(1, 0, At, B0); G_BAR; G_SCHED;
;             G_STAGE(G_SB(0, 1), b2 + hstepB, voffB);
;             G_WAIT_V(6); G_BAR; G_MMA(1, 1, At, B1); G_BAR;
.LBB0_1519:
	ds_read_b128 v[128:131], v187
	ds_read_b128 v[132:135], v187 offset:1024
	ds_read_b128 v[136:139], v187 offset:2048
	ds_read_b128 v[140:143], v187 offset:3072
	s_add_u32 s82, s80, 0x100
	s_addc_u32 s83, s81, 0
	s_cmp_eq_u32 s29, 28
	s_cselect_b32 s87, s73, s83
	s_cselect_b32 s86, s79, s82
	s_cselect_b32 s85, s71, s28
	s_cselect_b32 s84, vcc_lo, vcc_hi
	v_lshl_add_u64 v[200:201], s[80:81], 0, v[158:159]
	s_add_i32 m0, s27, 0xc000
	ds_read_b128 v[164:167], v188
	ds_read_b128 v[168:171], v188 offset:1024
	ds_read_b128 v[172:175], v188 offset:2048
	ds_read_b128 v[176:179], v188 offset:3072
	ds_read_b128 v[180:183], v188 offset:4096
	ds_read_b128 v[192:195], v188 offset:5120
	ds_read_b128 v[196:199], v188 offset:6144
	ds_read_b128 v[204:207], v188 offset:7168
	global_load_lds_dwordx4 v[200:201], off
	v_lshl_add_u64 v[200:201], s[80:81], 0, v[156:157]
	s_add_i32 m0, s27, 0xe000
	s_nop 0
	global_load_lds_dwordx4 v[200:201], off
	s_waitcnt lgkmcnt(8)
	s_barrier
	s_waitcnt lgkmcnt(0)
	s_setprio 1
	s_waitcnt lgkmcnt(0)
	v_mfma_f32_16x16x32_bf16 v[84:87], v[128:131], v[164:167], v[84:87]
	v_mfma_f32_16x16x32_bf16 v[12:15], v[136:139], v[164:167], v[12:15]
	v_mfma_f32_16x16x32_bf16 v[88:91], v[128:131], v[172:175], v[88:91]
	v_mfma_f32_16x16x32_bf16 v[60:63], v[136:139], v[172:175], v[60:63]
	v_mfma_f32_16x16x32_bf16 v[80:83], v[128:131], v[180:183], v[80:83]
	v_mfma_f32_16x16x32_bf16 v[52:55], v[136:139], v[180:183], v[52:55]
	v_mfma_f32_16x16x32_bf16 v[76:79], v[128:131], v[196:199], v[76:79]
	v_mfma_f32_16x16x32_bf16 v[44:47], v[136:139], v[196:199], v[44:47]
	v_mfma_f32_16x16x32_bf16 v[84:87], v[132:135], v[168:171], v[84:87]
	v_mfma_f32_16x16x32_bf16 v[12:15], v[140:143], v[168:171], v[12:15]
	v_mfma_f32_16x16x32_bf16 v[88:91], v[132:135], v[176:179], v[88:91]
	v_mfma_f32_16x16x32_bf16 v[60:63], v[140:143], v[176:179], v[60:63]
	v_mfma_f32_16x16x32_bf16 v[80:83], v[132:135], v[192:195], v[80:83]
	v_mfma_f32_16x16x32_bf16 v[52:55], v[140:143], v[192:195], v[52:55]
	v_mfma_f32_16x16x32_bf16 v[76:79], v[132:135], v[204:207], v[76:79]
	v_mfma_f32_16x16x32_bf16 v[44:47], v[140:143], v[204:207], v[44:47]
	s_setprio 0
	s_barrier
	s_add_i32 s80, s16, s5
	v_lshl_add_u64 v[200:201], s[84:85], 0, v[148:149]
	s_mov_b32 m0, s80
	ds_read_b128 v[208:211], v189
	ds_read_b128 v[212:215], v189 offset:1024
	ds_read_b128 v[216:219], v189 offset:2048
	ds_read_b128 v[220:223], v189 offset:3072
	global_load_lds_dwordx4 v[200:201], off
	v_lshl_add_u64 v[224:225], s[84:85], 0, v[144:145]
	s_add_i32 m0, s80, 0x2000
	s_nop 0
	global_load_lds_dwordx4 v[224:225], off
	s_barrier
	s_waitcnt lgkmcnt(0)
	s_setprio 1
	s_waitcnt lgkmcnt(0)
	v_mfma_f32_16x16x32_bf16 v[72:75], v[208:211], v[164:167], v[72:75]
	v_mfma_f32_16x16x32_bf16 v[8:11], v[216:219], v[164:167], v[8:11]
	v_mfma_f32_16x16x32_bf16 v[124:127], v[208:211], v[172:175], v[124:127]
	v_mfma_f32_16x16x32_bf16 v[56:59], v[216:219], v[172:175], v[56:59]
	v_mfma_f32_16x16x32_bf16 v[120:123], v[208:211], v[180:183], v[120:123]
	v_mfma_f32_16x16x32_bf16 v[48:51], v[216:219], v[180:183], v[48:51]
	v_mfma_f32_16x16x32_bf16 v[116:119], v[208:211], v[196:199], v[116:119]
	v_mfma_f32_16x16x32_bf16 v[40:43], v[216:219], v[196:199], v[40:43]
	v_mfma_f32_16x16x32_bf16 v[72:75], v[212:215], v[168:171], v[72:75]
	v_mfma_f32_16x16x32_bf16 v[8:11], v[220:223], v[168:171], v[8:11]
	v_mfma_f32_16x16x32_bf16 v[124:127], v[212:215], v[176:179], v[124:127]
	v_mfma_f32_16x16x32_bf16 v[56:59], v[220:223], v[176:179], v[56:59]
	v_mfma_f32_16x16x32_bf16 v[120:123], v[212:215], v[192:195], v[120:123]
	v_mfma_f32_16x16x32_bf16 v[48:51], v[220:223], v[192:195], v[48:51]
	v_mfma_f32_16x16x32_bf16 v[116:119], v[212:215], v[204:207], v[116:119]
	v_mfma_f32_16x16x32_bf16 v[40:43], v[220:223], v[204:207], v[40:43]
	s_setprio 0
	s_mov_b32 m0, s27
	v_lshl_add_u64 v[226:227], s[86:87], 0, v[150:151]
	s_barrier
	ds_read_b128 v[164:167], v188 offset:16384
	ds_read_b128 v[168:171], v188 offset:17408
	ds_read_b128 v[172:175], v188 offset:18432
	ds_read_b128 v[176:179], v188 offset:19456
	ds_read_b128 v[180:183], v188 offset:20480
	ds_read_b128 v[192:195], v188 offset:21504
	ds_read_b128 v[196:199], v188 offset:22528
	ds_read_b128 v[204:207], v188 offset:23552
	global_load_lds_dwordx4 v[226:227], off
	v_lshl_add_u64 v[228:229], s[86:87], 0, v[146:147]
	s_mov_b32 m0, s30
	s_nop 0
	global_load_lds_dwordx4 v[228:229], off
	s_barrier
	s_waitcnt lgkmcnt(0)
	s_setprio 1
	s_waitcnt lgkmcnt(0)
	v_mfma_f32_16x16x32_bf16 v[112:115], v[128:131], v[164:167], v[112:115]
	v_mfma_f32_16x16x32_bf16 v[36:39], v[136:139], v[164:167], v[36:39]
	v_mfma_f32_16x16x32_bf16 v[104:107], v[128:131], v[172:175], v[104:107]
	v_mfma_f32_16x16x32_bf16 v[28:31], v[136:139], v[172:175], v[28:31]
	v_mfma_f32_16x16x32_bf16 v[96:99], v[128:131], v[180:183], v[96:99]
	v_mfma_f32_16x16x32_bf16 v[20:23], v[136:139], v[180:183], v[20:23]
	v_mfma_f32_16x16x32_bf16 v[68:71], v[128:131], v[196:199], v[68:71]
	v_mfma_f32_16x16x32_bf16 v[4:7], v[136:139], v[196:199], v[4:7]
	v_mfma_f32_16x16x32_bf16 v[112:115], v[132:135], v[168:171], v[112:115]
	v_mfma_f32_16x16x32_bf16 v[36:39], v[140:143], v[168:171], v[36:39]
	v_mfma_f32_16x16x32_bf16 v[104:107], v[132:135], v[176:179], v[104:107]
	v_mfma_f32_16x16x32_bf16 v[28:31], v[140:143], v[176:179], v[28:31]
	v_mfma_f32_16x16x32_bf16 v[96:99], v[132:135], v[192:195], v[96:99]
	v_mfma_f32_16x16x32_bf16 v[20:23], v[140:143], v[192:195], v[20:23]
	v_mfma_f32_16x16x32_bf16 v[68:71], v[132:135], v[204:207], v[68:71]
	v_mfma_f32_16x16x32_bf16 v[4:7], v[140:143], v[204:207], v[4:7]
	s_setprio 0
	s_barrier
; #define G_STAGE(bufoff, gbase, voff) do { _Pragma("unroll") for (int _i = 0; _i < 2; ++_i) \
;         __builtin_amdgcn_global_load_lds((const unsigned*)((const char*)(gbase) + (voff)[_i]), (LAS unsigned*)(lds + (bufoff) + ldsw + _i * 8192), 16, 0, 0); } while (0)
; #define G_LDA(dst, b, h) do { _Pragma("unroll") for (int m = 0; m < 4; ++m) _Pragma("unroll") for (int k = 0; k < 2; ++k) dst[m][k] = *(const LAS bf16x8*)(lds + G_SA(b, h) + aoff + m * 2048 + k * 1024); } while (0)
; #define G_LDB(dst, b, h) do { _Pragma("unroll") for (int n = 0; n < 2; ++n) _Pragma("unroll") for (int k = 0; k < 2; ++k) dst[n][k] = *(const LAS bf16x8*)(lds + G_SB(b, h) + boff + n * 2048 + k * 1024); } while (0)
; #define G_MMA(ai, bj, At, Bt_) do { __builtin_amdgcn_s_setprio(1); _Pragma("unroll") for (int m = 0; m < 4; ++m) _Pragma("unroll") for (int n = 0; n < 2; ++n) _Pragma("unroll") for (int k = 0; k < 2; ++k) \
;         acc[ai][bj][m][n] = __builtin_amdgcn_mfma_f32_16x16x32_bf16(Bt_[n][k], At[m][k], acc[ai][bj][m][n], 0, 0, 0); __builtin_amdgcn_s_setprio(0); } while (0)
; #define G_WAIT_V(n) asm volatile("s_waitcnt vmcnt(" #n ")" ::: "memory")
; #define G_WAIT_L(n) asm volatile("s_waitcnt lgkmcnt(" #n ")" ::: "memory")
; #define G_BAR __builtin_amdgcn_s_barrier()
; #define G_SCHED __builtin_amdgcn_sched_barrier(0)
; template <class Epi, bool PERMROWS = false>
; DI void gemm_phase(LAS unsigned char* lds, const bf16_t* A, int lda, const bf16_t* Bt, int K, const Sched& S, const Epi& E) {
;     ...
;             G_WAIT_V(6); G_BAR; G_MMA(1, 1, At, B1); G_BAR;
;             G_LDB(B0, 1, 0); G_SCHED; G_LDA(At, 1, 0); G_STAGE(G_SA(0, 1), a2 + hstepA, voffA);
;             G_WAIT_L(8); G_BAR; G_WAIT_L(0); G_MMA(0, 0, At, B0); G_BAR; G_SCHED;
;             G_LDB(B1, 1, 1); G_STAGE(G_SB(1, 0), b3, voffB);
;             G_BAR; G_WAIT_L(0); G_MMA(0, 1, At, B1); G_BAR;
;             G_LDA(At, 1, 1); G_STAGE(G_SA(1, 0), a3, voffA);
;             G_BAR; G_WAIT_L(0); G_MMA(1, 0, At, B0); G_BAR; G_SCHED;
	s_add_u32 s80, s84, 0x80000
	s_addc_u32 s81, s85, 0
	s_add_i32 s90, s17, s5
	v_lshl_add_u64 v[128:129], s[80:81], 0, v[148:149]
	s_mov_b32 m0, s90
	s_nop 0
	global_load_lds_dwordx4 v[128:129], off
	v_lshl_add_u64 v[128:129], s[80:81], 0, v[144:145]
	s_add_i32 m0, s90, 0x2000
	s_nop 0
	global_load_lds_dwordx4 v[128:129], off
	s_waitcnt vmcnt(6)
	s_barrier
	s_setprio 1
	v_mfma_f32_16x16x32_bf16 v[108:111], v[208:211], v[164:167], v[108:111]
	v_mfma_f32_16x16x32_bf16 v[32:35], v[216:219], v[164:167], v[32:35]
	v_mfma_f32_16x16x32_bf16 v[100:103], v[208:211], v[172:175], v[100:103]
	v_mfma_f32_16x16x32_bf16 v[24:27], v[216:219], v[172:175], v[24:27]
	v_mfma_f32_16x16x32_bf16 v[92:95], v[208:211], v[180:183], v[92:95]
	v_mfma_f32_16x16x32_bf16 v[16:19], v[216:219], v[180:183], v[16:19]
	v_mfma_f32_16x16x32_bf16 v[64:67], v[208:211], v[196:199], v[64:67]
	v_mfma_f32_16x16x32_bf16 v[0:3], v[216:219], v[196:199], v[0:3]
	v_mfma_f32_16x16x32_bf16 v[108:111], v[212:215], v[168:171], v[108:111]
	v_mfma_f32_16x16x32_bf16 v[32:35], v[220:223], v[168:171], v[32:35]
	v_mfma_f32_16x16x32_bf16 v[100:103], v[212:215], v[176:179], v[100:103]
	v_mfma_f32_16x16x32_bf16 v[24:27], v[220:223], v[176:179], v[24:27]
	v_mfma_f32_16x16x32_bf16 v[92:95], v[212:215], v[192:195], v[92:95]
	v_mfma_f32_16x16x32_bf16 v[16:19], v[220:223], v[192:195], v[16:19]
	v_mfma_f32_16x16x32_bf16 v[64:67], v[212:215], v[204:207], v[64:67]
	v_mfma_f32_16x16x32_bf16 v[0:3], v[220:223], v[204:207], v[0:3]
	s_setprio 0
	s_add_i32 s90, 0, 0x18000
	v_add_u32_e32 v140, s90, v185
	s_barrier
	ds_read_b128 v[128:131], v140
	ds_read_b128 v[132:135], v140 offset:1024
	ds_read_b128 v[136:139], v140 offset:2048
	ds_read_b128 v[140:143], v140 offset:3072
	s_add_u32 s80, s86, 0x4000
	s_addc_u32 s81, s87, 0
	s_mov_b32 m0, s31
	v_lshl_add_u64 v[208:209], s[80:81], 0, v[150:151]
	ds_read_b128 v[164:167], v188 offset:32768
	ds_read_b128 v[168:171], v188 offset:33792
	ds_read_b128 v[172:175], v188 offset:34816
	ds_read_b128 v[176:179], v188 offset:35840
	ds_read_b128 v[180:183], v188 offset:36864
	ds_read_b128 v[192:195], v188 offset:37888
	ds_read_b128 v[196:199], v188 offset:38912
	ds_read_b128 v[204:207], v188 offset:39936
	global_load_lds_dwordx4 v[208:209], off
	v_lshl_add_u64 v[208:209], s[80:81], 0, v[146:147]
	s_mov_b32 m0, s34
	s_nop 0
	global_load_lds_dwordx4 v[208:209], off
	s_waitcnt lgkmcnt(8)
	s_barrier
	s_waitcnt lgkmcnt(0)
	s_setprio 1
	s_waitcnt lgkmcnt(0)
	v_mfma_f32_16x16x32_bf16 v[84:87], v[128:131], v[164:167], v[84:87]
	v_mfma_f32_16x16x32_bf16 v[12:15], v[136:139], v[164:167], v[12:15]
	v_mfma_f32_16x16x32_bf16 v[88:91], v[128:131], v[172:175], v[88:91]
	v_mfma_f32_16x16x32_bf16 v[60:63], v[136:139], v[172:175], v[60:63]
	v_mfma_f32_16x16x32_bf16 v[80:83], v[128:131], v[180:183], v[80:83]
	v_mfma_f32_16x16x32_bf16 v[52:55], v[136:139], v[180:183], v[52:55]
	v_mfma_f32_16x16x32_bf16 v[76:79], v[128:131], v[196:199], v[76:79]
	v_mfma_f32_16x16x32_bf16 v[44:47], v[136:139], v[196:199], v[44:47]
	v_mfma_f32_16x16x32_bf16 v[84:87], v[132:135], v[168:171], v[84:87]
	v_mfma_f32_16x16x32_bf16 v[12:15], v[140:143], v[168:171], v[12:15]
	v_mfma_f32_16x16x32_bf16 v[88:91], v[132:135], v[176:179], v[88:91]
	v_mfma_f32_16x16x32_bf16 v[60:63], v[140:143], v[176:179], v[60:63]
	v_mfma_f32_16x16x32_bf16 v[80:83], v[132:135], v[192:195], v[80:83]
	v_mfma_f32_16x16x32_bf16 v[52:55], v[140:143], v[192:195], v[52:55]
	v_mfma_f32_16x16x32_bf16 v[76:79], v[132:135], v[204:207], v[76:79]
	v_mfma_f32_16x16x32_bf16 v[44:47], v[140:143], v[204:207], v[44:47]
	s_setprio 0
	s_barrier
	s_add_i32 s86, 0, 0x1c000
	s_add_i32 s80, s90, s5
	v_add_u32_e32 v191, s86, v185
	v_lshl_add_u64 v[200:201], v[200:201], 0, s[18:19]
	s_mov_b32 m0, s80
	ds_read_b128 v[208:211], v191
	ds_read_b128 v[212:215], v191 offset:1024
	ds_read_b128 v[216:219], v191 offset:2048
	ds_read_b128 v[220:223], v191 offset:3072
	global_load_lds_dwordx4 v[200:201], off
	v_lshl_add_u64 v[200:201], v[224:225], 0, s[18:19]
	s_add_i32 m0, s80, 0x2000
	s_nop 0
	global_load_lds_dwordx4 v[200:201], off
	s_barrier
	s_waitcnt lgkmcnt(0)
	s_setprio 1
	s_waitcnt lgkmcnt(0)
	v_mfma_f32_16x16x32_bf16 v[72:75], v[208:211], v[164:167], v[72:75]
	v_mfma_f32_16x16x32_bf16 v[8:11], v[216:219], v[164:167], v[8:11]
	v_mfma_f32_16x16x32_bf16 v[124:127], v[208:211], v[172:175], v[124:127]
	v_mfma_f32_16x16x32_bf16 v[56:59], v[216:219], v[172:175], v[56:59]
	v_mfma_f32_16x16x32_bf16 v[120:123], v[208:211], v[180:183], v[120:123]
	v_mfma_f32_16x16x32_bf16 v[48:51], v[216:219], v[180:183], v[48:51]
	v_mfma_f32_16x16x32_bf16 v[116:119], v[208:211], v[196:199], v[116:119]
	v_mfma_f32_16x16x32_bf16 v[40:43], v[216:219], v[196:199], v[40:43]
	v_mfma_f32_16x16x32_bf16 v[72:75], v[212:215], v[168:171], v[72:75]
	v_mfma_f32_16x16x32_bf16 v[8:11], v[220:223], v[168:171], v[8:11]
	v_mfma_f32_16x16x32_bf16 v[124:127], v[212:215], v[176:179], v[124:127]
	v_mfma_f32_16x16x32_bf16 v[56:59], v[220:223], v[176:179], v[56:59]
	v_mfma_f32_16x16x32_bf16 v[120:123], v[212:215], v[192:195], v[120:123]
	v_mfma_f32_16x16x32_bf16 v[48:51], v[220:223], v[192:195], v[48:51]
	v_mfma_f32_16x16x32_bf16 v[116:119], v[212:215], v[204:207], v[116:119]
	v_mfma_f32_16x16x32_bf16 v[40:43], v[220:223], v[204:207], v[40:43]
	s_setprio 0
	s_mov_b32 m0, s89
	v_lshl_add_u64 v[200:201], v[226:227], 0, s[18:19]
	s_barrier
	ds_read_b128 v[164:167], v188 offset:49152
	ds_read_b128 v[168:171], v188 offset:50176
	ds_read_b128 v[172:175], v188 offset:51200
	ds_read_b128 v[176:179], v188 offset:52224
	ds_read_b128 v[180:183], v188 offset:53248
	ds_read_b128 v[192:195], v188 offset:54272
	ds_read_b128 v[196:199], v188 offset:55296
	ds_read_b128 v[204:207], v188 offset:56320
	global_load_lds_dwordx4 v[200:201], off
	v_lshl_add_u64 v[200:201], v[228:229], 0, s[18:19]
	s_mov_b32 m0, s96
	s_nop 0
	global_load_lds_dwordx4 v[200:201], off
	s_barrier
; #define G_STAGE(bufoff, gbase, voff) do { _Pragma("unroll") for (int _i = 0; _i < 2; ++_i) \
;         __builtin_amdgcn_global_load_lds((const unsigned*)((const char*)(gbase) + (voff)[_i]), (LAS unsigned*)(lds + (bufoff) + ldsw + _i * 8192), 16, 0, 0); } while (0)
; #define G_MMA(ai, bj, At, Bt_) do { __builtin_amdgcn_s_setprio(1); _Pragma("unroll") for (int m = 0; m < 4; ++m) _Pragma("unroll") for (int n = 0; n < 2; ++n) _Pragma("unroll") for (int k = 0; k < 2; ++k) \
;         acc[ai][bj][m][n] = __builtin_amdgcn_mfma_f32_16x16x32_bf16(Bt_[n][k], At[m][k], acc[ai][bj][m][n], 0, 0, 0); __builtin_amdgcn_s_setprio(0); } while (0)
; #define G_WAIT_V(n) asm volatile("s_waitcnt vmcnt(" #n ")" ::: "memory")
; #define G_WAIT_L(n) asm volatile("s_waitcnt lgkmcnt(" #n ")" ::: "memory")
; #define G_BAR __builtin_amdgcn_s_barrier()
; #define G_SCHED __builtin_amdgcn_sched_barrier(0)
; template <class Epi, bool PERMROWS = false>
; DI void gemm_phase(LAS unsigned char* lds, const bf16_t* A, int lda, const bf16_t* Bt, int K, const Sched& S, const Epi& E) {
;     ...
;             G_BAR; G_WAIT_L(0); G_MMA(1, 0, At, B0); G_BAR; G_SCHED;
;             G_STAGE(G_SB(1, 1), b3 + hstepB, voffB);
;             G_WAIT_V(6); G_BAR; G_MMA(1, 1, At, B1); G_BAR;
;     DI void operator()(const f32x4 (&acc)[2][2][4][2], const Unit& u, int wr, int wc, int fr, int fq) const {
;         bf16_t* G = (bf16_t*)(ws + WS_G);
;         float* EA = (float*)(ws + WS_EDGE); float* EP = EA + (size_t)36 * 4 * DFF; float* EU = EP + (size_t)36 * 4 * DFF;
;         const int tok0 = (wr * 16 + fr) * 8;
;         const size_t row0 = (size_t)u.pm * BM + tok0;
;         const bool e_lo = (fr == 0), e_hi = (fr == 15);
; #pragma unroll
;         for (int n = 0; n < 2; ++n) {
;             const int col = u.pn * 128 + wc * 32 + n * 16 + 4 * fq;
;             const f32x4 w0 = *(const f32x4*)(cw + col), w1 = *(const f32x4*)(cw + DFF + col), w2 = *(const f32x4*)(cw + 2 * DFF + col), bb = *(const f32x4*)(cb + col);
;             f32x4 g[8];
;             f32x4 ed_a, ed_p, ed_u;
	s_waitcnt lgkmcnt(0)
	s_setprio 1
	s_waitcnt lgkmcnt(0)
	v_mfma_f32_16x16x32_bf16 v[112:115], v[128:131], v[164:167], v[112:115]
	v_mfma_f32_16x16x32_bf16 v[36:39], v[136:139], v[164:167], v[36:39]
	v_mfma_f32_16x16x32_bf16 v[104:107], v[128:131], v[172:175], v[104:107]
	v_mfma_f32_16x16x32_bf16 v[28:31], v[136:139], v[172:175], v[28:31]
	v_mfma_f32_16x16x32_bf16 v[96:99], v[128:131], v[180:183], v[96:99]
	v_mfma_f32_16x16x32_bf16 v[20:23], v[136:139], v[180:183], v[20:23]
	v_mfma_f32_16x16x32_bf16 v[68:71], v[128:131], v[196:199], v[68:71]
	v_mfma_f32_16x16x32_bf16 v[4:7], v[136:139], v[196:199], v[4:7]
	v_mfma_f32_16x16x32_bf16 v[112:115], v[132:135], v[168:171], v[112:115]
	v_mfma_f32_16x16x32_bf16 v[36:39], v[140:143], v[168:171], v[36:39]
	v_mfma_f32_16x16x32_bf16 v[104:107], v[132:135], v[176:179], v[104:107]
	v_mfma_f32_16x16x32_bf16 v[28:31], v[140:143], v[176:179], v[28:31]
	v_mfma_f32_16x16x32_bf16 v[96:99], v[132:135], v[192:195], v[96:99]
	v_mfma_f32_16x16x32_bf16 v[20:23], v[140:143], v[192:195], v[20:23]
	v_mfma_f32_16x16x32_bf16 v[68:71], v[132:135], v[204:207], v[68:71]
	v_mfma_f32_16x16x32_bf16 v[4:7], v[140:143], v[204:207], v[4:7]
	s_setprio 0
	s_barrier
	s_add_u32 s80, s84, 0x80080
	s_addc_u32 s81, s85, 0
	s_add_i32 s84, s86, s5
	v_lshl_add_u64 v[128:129], s[80:81], 0, v[148:149]
	s_mov_b32 m0, s84
	s_nop 0
	global_load_lds_dwordx4 v[128:129], off
	v_lshl_add_u64 v[128:129], s[80:81], 0, v[144:145]
	s_add_i32 m0, s84, 0x2000
	s_nop 0
	global_load_lds_dwordx4 v[128:129], off
	s_waitcnt vmcnt(6)
	s_barrier
	s_setprio 1
	v_mfma_f32_16x16x32_bf16 v[108:111], v[208:211], v[164:167], v[108:111]
	v_mfma_f32_16x16x32_bf16 v[32:35], v[216:219], v[164:167], v[32:35]
	v_mfma_f32_16x16x32_bf16 v[100:103], v[208:211], v[172:175], v[100:103]
	v_mfma_f32_16x16x32_bf16 v[24:27], v[216:219], v[172:175], v[24:27]
	v_mfma_f32_16x16x32_bf16 v[92:95], v[208:211], v[180:183], v[92:95]
	v_mfma_f32_16x16x32_bf16 v[16:19], v[216:219], v[180:183], v[16:19]
	v_mfma_f32_16x16x32_bf16 v[64:67], v[208:211], v[196:199], v[64:67]
	v_mfma_f32_16x16x32_bf16 v[0:3], v[216:219], v[196:199], v[0:3]
	v_mfma_f32_16x16x32_bf16 v[108:111], v[212:215], v[168:171], v[108:111]
	v_mfma_f32_16x16x32_bf16 v[32:35], v[220:223], v[168:171], v[32:35]
	v_mfma_f32_16x16x32_bf16 v[100:103], v[212:215], v[176:179], v[100:103]
	v_mfma_f32_16x16x32_bf16 v[24:27], v[220:223], v[176:179], v[24:27]
	v_mfma_f32_16x16x32_bf16 v[92:95], v[212:215], v[192:195], v[92:95]
	v_mfma_f32_16x16x32_bf16 v[16:19], v[220:223], v[192:195], v[16:19]
	v_mfma_f32_16x16x32_bf16 v[64:67], v[212:215], v[204:207], v[64:67]
	v_mfma_f32_16x16x32_bf16 v[0:3], v[220:223], v[204:207], v[0:3]
	s_setprio 0
	s_add_i32 s29, s29, 2
	s_add_u32 vcc_hi, vcc_hi, 0x100
	s_addc_u32 s28, s28, 0
	s_cmp_gt_u32 s29, 29
	s_mov_b64 s[80:81], s[82:83]
	s_barrier
	s_cbranch_scc0 .LBB0_1519
	s_mov_b32 s71, s91
	v_and_b32_e32 v131, 15, v202
	v_bfe_u32 v134, v202, 8, 1
	v_bfe_u32 v135, v202, 6, 2
	v_bfe_u32 v138, v202, 4, 2
	s_lshl_b32 s29, s43, 7
	v_lshlrev_b32_e32 v139, 5, v135
	v_lshl_add_u32 v139, v138, 2, v139
	v_add_u32_e32 v139, s29, v139
	v_lshlrev_b32_e32 v128, 2, v139
	v_lshl_add_u32 v140, v134, 4, v131
	v_mul_u32_u24_e32 v129, 0x16000, v140
	v_lshl_add_u32 v129, v139, 1, v129
	v_cmp_eq_u32_e64 s[84:85], 0, v131
	v_cmp_eq_u32_e64 s[86:87], 15, v131
	v_lshlrev_b32_e32 v130, 1, v134
	v_cndmask_b32_e64 v141, 0, 1, s[86:87]
	v_add_u32_e32 v130, v130, v141
	v_mul_u32_u24_e32 v130, 0x5800, v130
	v_add_u32_e32 v130, v130, v128
	v_mov_b32_e32 v132, 0xbfb8aa3b
	v_mov_b32_e32 v133, 0xbfb8aa3b
	s_mov_b64 s[82:83], s[38:39]
	global_load_dwordx4 v[204:207], v128, s[82:83] offset:0
	global_load_dwordx4 v[220:223], v128, s[82:83] offset:64
	s_add_u32 s82, s82, 0x5800
	s_addc_u32 s83, s83, 0
	global_load_dwordx4 v[208:211], v128, s[82:83] offset:0
	global_load_dwordx4 v[224:227], v128, s[82:83] offset:64
	s_add_u32 s82, s82, 0x5800
	s_addc_u32 s83, s83, 0
	global_load_dwordx4 v[212:215], v128, s[82:83] offset:0
	global_load_dwordx4 v[228:231], v128, s[82:83] offset:64
	global_load_dwordx4 v[216:219], v128, s[40:41] offset:0
	global_load_dwordx4 v[232:235], v128, s[40:41] offset:64
	s_mul_i32 s29, s78, 0x2c0000
	s_mul_i32 s32, s78, 0x16000
	s_waitcnt vmcnt(0)
; DI void st_bf16x4(bf16_t* p, f32x4 v) { u32x2 w; w.x = cvt_pk_bf16(v[0], v[1]); w.y = cvt_pk_bf16(v[2], v[3]); *(u32x2*)p = w; }
; DI float silu(float v) { return v * __builtin_amdgcn_rcpf(1.f + __builtin_amdgcn_exp2f(-1.4426950408889634f * v)); }
;     DI void operator()(const f32x4 (&acc)[2][2][4][2], const Unit& u, int wr, int wc, int fr, int fq) const {
;     ...
; #pragma unroll
;             for (int j = 0; j < 4; ++j) {
;                 float a[8], uu[8];
; #pragma unroll
;                 for (int k = 0; k < 8; ++k) { a[k] = acc[k >> 2][0][k & 3][n][j]; uu[k] = acc[k >> 2][1][k & 3][n][j]; }
;                 const float aprev = __shfl_up(a[7], 1), anext = __shfl_down(a[0], 1);
; #pragma unroll
;                 for (int k = 0; k < 8; ++k) {
;                     const float c = bb[j] + w0[j] * (k > 0 ? a[k - 1] : aprev) + w1[j] * a[k] + w2[j] * (k < 7 ? a[k + 1] : anext);
;                     g[k][j] = silu(c) * uu[k];
;                 }
;                 if (e_lo) { ed_a[j] = a[0]; ed_p[j] = bb[j] + w1[j] * a[0] + w2[j] * a[1]; ed_u[j] = uu[0]; }
;                 if (e_hi) { ed_a[j] = a[7]; ed_p[j] = bb[j] + w0[j] * a[6] + w1[j] * a[7]; ed_u[j] = uu[7]; }
;             }
; #pragma unroll
;             for (int k = 0; k < 8; ++k) {
;                 if ((k == 0 && e_lo) || (k == 7 && e_hi)) continue;
;                 st_bf16x4(G + (row0 + k) * DFF + col, g[k]);
;             }
;             if (e_lo || e_hi) {
;                 const size_t eo = ((size_t)u.pm * 4 + wr * 2 + (e_hi ? 1 : 0)) * DFF + col;
;                 *(f32x4*)(EA + eo) = ed_a; *(f32x4*)(EP + eo) = ed_p; *(f32x4*)(EU + eo) = ed_u;
	v_mov_b32_dpp v164, v68 row_shr:1 row_mask:0xf bank_mask:0xf bound_ctrl:0
	v_mov_b32_dpp v165, v69 row_shr:1 row_mask:0xf bank_mask:0xf bound_ctrl:0
	v_mov_b32_dpp v166, v70 row_shr:1 row_mask:0xf bank_mask:0xf bound_ctrl:0
	v_mov_b32_dpp v167, v71 row_shr:1 row_mask:0xf bank_mask:0xf bound_ctrl:0
	v_mov_b32_dpp v168, v84 row_shl:1 row_mask:0xf bank_mask:0xf bound_ctrl:0
	v_mov_b32_dpp v169, v85 row_shl:1 row_mask:0xf bank_mask:0xf bound_ctrl:0
	v_mov_b32_dpp v170, v86 row_shl:1 row_mask:0xf bank_mask:0xf bound_ctrl:0
	v_mov_b32_dpp v171, v87 row_shl:1 row_mask:0xf bank_mask:0xf bound_ctrl:0
	s_mov_b64 exec, s[84:85]
	v_pk_fma_f32 v[172:173], v[208:209], v[84:85], v[216:217]
	v_pk_fma_f32 v[172:173], v[212:213], v[88:89], v[172:173]
	v_pk_fma_f32 v[174:175], v[210:211], v[86:87], v[218:219]
	v_pk_fma_f32 v[174:175], v[214:215], v[90:91], v[174:175]
	s_add_u32 s82, s50, 0x113a0000
	s_addc_u32 s83, s51, 0
	s_add_u32 s82, s82, s32
	s_addc_u32 s83, s83, 0
	global_store_dwordx4 v130, v[84:87], s[82:83] offset:0
	s_add_u32 s82, s82, 0x318000
	s_addc_u32 s83, s83, 0
	global_store_dwordx4 v130, v[172:175], s[82:83] offset:0
	s_add_u32 s82, s82, 0x318000
	s_addc_u32 s83, s83, 0
	global_store_dwordx4 v130, v[72:75], s[82:83] offset:0
	s_nop 1
	s_mov_b64 exec, s[86:87]
	v_pk_fma_f32 v[172:173], v[204:205], v[96:97], v[216:217]
	v_pk_fma_f32 v[172:173], v[208:209], v[68:69], v[172:173]
	v_pk_fma_f32 v[174:175], v[206:207], v[98:99], v[218:219]
	v_pk_fma_f32 v[174:175], v[210:211], v[70:71], v[174:175]
	s_add_u32 s82, s50, 0x113a0000
	s_addc_u32 s83, s51, 0
	s_add_u32 s82, s82, s32
	s_addc_u32 s83, s83, 0
	global_store_dwordx4 v130, v[68:71], s[82:83] offset:0
	s_add_u32 s82, s82, 0x318000
	s_addc_u32 s83, s83, 0
	global_store_dwordx4 v130, v[172:175], s[82:83] offset:0
	s_add_u32 s82, s82, 0x318000
	s_addc_u32 s83, s83, 0
	global_store_dwordx4 v130, v[64:67], s[82:83] offset:0
	s_nop 1
	s_mov_b64 exec, -1
	s_add_u32 s80, s50, 0x1d9a0000
	s_addc_u32 s81, s51, 0
	s_add_u32 s80, s80, s29
	s_addc_u32 s81, s81, 0
	v_pk_fma_f32 v[236:237], v[204:205], v[164:165], v[216:217]
	v_pk_fma_f32 v[236:237], v[208:209], v[84:85], v[236:237]
	v_pk_fma_f32 v[236:237], v[212:213], v[88:89], v[236:237]
	v_pk_fma_f32 v[238:239], v[206:207], v[166:167], v[218:219]
	v_pk_fma_f32 v[238:239], v[210:211], v[86:87], v[238:239]
	v_pk_fma_f32 v[238:239], v[214:215], v[90:91], v[238:239]
	v_pk_mul_f32 v[244:245], v[236:237], v[132:133]
	v_pk_mul_f32 v[246:247], v[238:239], v[132:133]
	v_exp_f32_e32 v244, v244
	v_exp_f32_e32 v245, v245
	v_exp_f32_e32 v246, v246
	v_exp_f32_e32 v247, v247
	v_pk_add_f32 v[244:245], v[244:245], 1.0 op_sel_hi:[1,0]
	v_pk_add_f32 v[246:247], v[246:247], 1.0 op_sel_hi:[1,0]
	v_rcp_f32_e32 v244, v244
	v_rcp_f32_e32 v245, v245
	v_rcp_f32_e32 v246, v246
	v_rcp_f32_e32 v247, v247
	v_pk_mul_f32 v[236:237], v[236:237], v[244:245]
	v_pk_mul_f32 v[238:239], v[238:239], v[246:247]
	v_pk_mul_f32 v[72:73], v[72:73], v[236:237]
	v_pk_mul_f32 v[74:75], v[74:75], v[238:239]
	v_cvt_pk_bf16_f32 v72, v72, v73
	v_cvt_pk_bf16_f32 v73, v74, v75
	s_andn2_b64 exec, exec, s[84:85]
	global_store_dwordx2 v129, v[72:73], s[80:81] offset:0
	s_mov_b64 exec, -1
	s_add_u32 s80, s80, 0x2c00
	s_addc_u32 s81, s81, 0
	v_pk_fma_f32 v[236:237], v[204:205], v[84:85], v[216:217]
	v_pk_fma_f32 v[236:237], v[208:209], v[88:89], v[236:237]
	v_pk_fma_f32 v[236:237], v[212:213], v[80:81], v[236:237]
	v_pk_fma_f32 v[238:239], v[206:207], v[86:87], v[218:219]
	v_pk_fma_f32 v[238:239], v[210:211], v[90:91], v[238:239]
	v_pk_fma_f32 v[238:239], v[214:215], v[82:83], v[238:239]
	v_pk_mul_f32 v[244:245], v[236:237], v[132:133]
	v_pk_mul_f32 v[246:247], v[238:239], v[132:133]
	v_exp_f32_e32 v244, v244
	v_exp_f32_e32 v245, v245
	v_exp_f32_e32 v246, v246
	v_exp_f32_e32 v247, v247
	v_pk_add_f32 v[244:245], v[244:245], 1.0 op_sel_hi:[1,0]
	v_pk_add_f32 v[246:247], v[246:247], 1.0 op_sel_hi:[1,0]
	v_rcp_f32_e32 v244, v244
	v_rcp_f32_e32 v245, v245
	v_rcp_f32_e32 v246, v246
	v_rcp_f32_e32 v247, v247
	v_pk_mul_f32 v[236:237], v[236:237], v[244:245]
	v_pk_mul_f32 v[238:239], v[238:239], v[246:247]
	v_pk_mul_f32 v[124:125], v[124:125], v[236:237]
	v_pk_mul_f32 v[126:127], v[126:127], v[238:239]
	v_cvt_pk_bf16_f32 v124, v124, v125
	v_cvt_pk_bf16_f32 v125, v126, v127
	global_store_dwordx2 v129, v[124:125], s[80:81] offset:0
	s_add_u32 s80, s80, 0x2c00
	s_addc_u32 s81, s81, 0
	v_pk_fma_f32 v[236:237], v[204:205], v[88:89], v[216:217]
	v_pk_fma_f32 v[236:237], v[208:209], v[80:81], v[236:237]
	v_pk_fma_f32 v[236:237], v[212:213], v[76:77], v[236:237]
	v_pk_fma_f32 v[238:239], v[206:207], v[90:91], v[218:219]
	v_pk_fma_f32 v[238:239], v[210:211], v[82:83], v[238:239]
	v_pk_fma_f32 v[238:239], v[214:215], v[78:79], v[238:239]
	v_pk_mul_f32 v[244:245], v[236:237], v[132:133]
	v_pk_mul_f32 v[246:247], v[238:239], v[132:133]
	v_exp_f32_e32 v244, v244
	v_exp_f32_e32 v245, v245
	v_exp_f32_e32 v246, v246
	v_exp_f32_e32 v247, v247
	v_pk_add_f32 v[244:245], v[244:245], 1.0 op_sel_hi:[1,0]
	v_pk_add_f32 v[246:247], v[246:247], 1.0 op_sel_hi:[1,0]
	v_rcp_f32_e32 v244, v244
	v_rcp_f32_e32 v245, v245
	v_rcp_f32_e32 v246, v246
	v_rcp_f32_e32 v247, v247
	v_pk_mul_f32 v[236:237], v[236:237], v[244:245]
	v_pk_mul_f32 v[238:239], v[238:239], v[246:247]
	v_pk_mul_f32 v[120:121], v[120:121], v[236:237]
	v_pk_mul_f32 v[122:123], v[122:123], v[238:239]
	v_cvt_pk_bf16_f32 v120, v120, v121
	v_cvt_pk_bf16_f32 v121, v122, v123
	global_store_dwordx2 v129, v[120:121], s[80:81] offset:0
	s_add_u32 s80, s80, 0x2c00
	s_addc_u32 s81, s81, 0
	v_pk_fma_f32 v[236:237], v[204:205], v[80:81], v[216:217]
	v_pk_fma_f32 v[236:237], v[208:209], v[76:77], v[236:237]
; DI float silu(float v) { return v * __builtin_amdgcn_rcpf(1.f + __builtin_amdgcn_exp2f(-1.4426950408889634f * v)); }
; DI void st_bf16x4(bf16_t* p, f32x4 v) { u32x2 w; w.x = cvt_pk_bf16(v[0], v[1]); w.y = cvt_pk_bf16(v[2], v[3]); *(u32x2*)p = w; }
;     DI void operator()(const f32x4 (&acc)[2][2][4][2], const Unit& u, int wr, int wc, int fr, int fq) const {
;     ...
; #pragma unroll
;                 for (int k = 0; k < 8; ++k) {
;                     const float c = bb[j] + w0[j] * (k > 0 ? a[k - 1] : aprev) + w1[j] * a[k] + w2[j] * (k < 7 ? a[k + 1] : anext);
;                     g[k][j] = silu(c) * uu[k];
;                 }
;                 if (e_lo) { ed_a[j] = a[0]; ed_p[j] = bb[j] + w1[j] * a[0] + w2[j] * a[1]; ed_u[j] = uu[0]; }
;                 if (e_hi) { ed_a[j] = a[7]; ed_p[j] = bb[j] + w0[j] * a[6] + w1[j] * a[7]; ed_u[j] = uu[7]; }
;             }
; #pragma unroll
;             for (int k = 0; k < 8; ++k) {
;                 if ((k == 0 && e_lo) || (k == 7 && e_hi)) continue;
;                 st_bf16x4(G + (row0 + k) * DFF + col, g[k]);
	v_pk_fma_f32 v[236:237], v[212:213], v[112:113], v[236:237]
	v_pk_fma_f32 v[238:239], v[206:207], v[82:83], v[218:219]
	v_pk_fma_f32 v[238:239], v[210:211], v[78:79], v[238:239]
	v_pk_fma_f32 v[238:239], v[214:215], v[114:115], v[238:239]
	v_pk_mul_f32 v[244:245], v[236:237], v[132:133]
	v_pk_mul_f32 v[246:247], v[238:239], v[132:133]
	v_exp_f32_e32 v244, v244
	v_exp_f32_e32 v245, v245
	v_exp_f32_e32 v246, v246
	v_exp_f32_e32 v247, v247
	v_pk_add_f32 v[244:245], v[244:245], 1.0 op_sel_hi:[1,0]
	v_pk_add_f32 v[246:247], v[246:247], 1.0 op_sel_hi:[1,0]
	v_rcp_f32_e32 v244, v244
	v_rcp_f32_e32 v245, v245
	v_rcp_f32_e32 v246, v246
	v_rcp_f32_e32 v247, v247
	v_pk_mul_f32 v[236:237], v[236:237], v[244:245]
	v_pk_mul_f32 v[238:239], v[238:239], v[246:247]
	v_pk_mul_f32 v[116:117], v[116:117], v[236:237]
	v_pk_mul_f32 v[118:119], v[118:119], v[238:239]
	v_cvt_pk_bf16_f32 v116, v116, v117
	v_cvt_pk_bf16_f32 v117, v118, v119
	global_store_dwordx2 v129, v[116:117], s[80:81] offset:0
	s_add_u32 s80, s80, 0x2c00
	s_addc_u32 s81, s81, 0
	v_pk_fma_f32 v[236:237], v[204:205], v[76:77], v[216:217]
	v_pk_fma_f32 v[236:237], v[208:209], v[112:113], v[236:237]
	v_pk_fma_f32 v[236:237], v[212:213], v[104:105], v[236:237]
	v_pk_fma_f32 v[238:239], v[206:207], v[78:79], v[218:219]
	v_pk_fma_f32 v[238:239], v[210:211], v[114:115], v[238:239]
	v_pk_fma_f32 v[238:239], v[214:215], v[106:107], v[238:239]
	v_pk_mul_f32 v[244:245], v[236:237], v[132:133]
	v_pk_mul_f32 v[246:247], v[238:239], v[132:133]
	v_exp_f32_e32 v244, v244
	v_exp_f32_e32 v245, v245
	v_exp_f32_e32 v246, v246
	v_exp_f32_e32 v247, v247
	v_pk_add_f32 v[244:245], v[244:245], 1.0 op_sel_hi:[1,0]
	v_pk_add_f32 v[246:247], v[246:247], 1.0 op_sel_hi:[1,0]
	v_rcp_f32_e32 v244, v244
	v_rcp_f32_e32 v245, v245
	v_rcp_f32_e32 v246, v246
	v_rcp_f32_e32 v247, v247
	v_pk_mul_f32 v[236:237], v[236:237], v[244:245]
	v_pk_mul_f32 v[238:239], v[238:239], v[246:247]
	v_pk_mul_f32 v[108:109], v[108:109], v[236:237]
	v_pk_mul_f32 v[110:111], v[110:111], v[238:239]
	v_cvt_pk_bf16_f32 v108, v108, v109
	v_cvt_pk_bf16_f32 v109, v110, v111
	global_store_dwordx2 v129, v[108:109], s[80:81] offset:0
	s_add_u32 s80, s80, 0x2c00
	s_addc_u32 s81, s81, 0
	v_pk_fma_f32 v[236:237], v[204:205], v[112:113], v[216:217]
	v_pk_fma_f32 v[236:237], v[208:209], v[104:105], v[236:237]
	v_pk_fma_f32 v[236:237], v[212:213], v[96:97], v[236:237]
	v_pk_fma_f32 v[238:239], v[206:207], v[114:115], v[218:219]
	v_pk_fma_f32 v[238:239], v[210:211], v[106:107], v[238:239]
	v_pk_fma_f32 v[238:239], v[214:215], v[98:99], v[238:239]
	v_pk_mul_f32 v[244:245], v[236:237], v[132:133]
	v_pk_mul_f32 v[246:247], v[238:239], v[132:133]
	v_exp_f32_e32 v244, v244
	v_exp_f32_e32 v245, v245
	v_exp_f32_e32 v246, v246
	v_exp_f32_e32 v247, v247
	v_pk_add_f32 v[244:245], v[244:245], 1.0 op_sel_hi:[1,0]
	v_pk_add_f32 v[246:247], v[246:247], 1.0 op_sel_hi:[1,0]
	v_rcp_f32_e32 v244, v244
	v_rcp_f32_e32 v245, v245
	v_rcp_f32_e32 v246, v246
	v_rcp_f32_e32 v247, v247
	v_pk_mul_f32 v[236:237], v[236:237], v[244:245]
	v_pk_mul_f32 v[238:239], v[238:239], v[246:247]
	v_pk_mul_f32 v[100:101], v[100:101], v[236:237]
	v_pk_mul_f32 v[102:103], v[102:103], v[238:239]
	v_cvt_pk_bf16_f32 v100, v100, v101
	v_cvt_pk_bf16_f32 v101, v102, v103
	global_store_dwordx2 v129, v[100:101], s[80:81] offset:0
	s_add_u32 s80, s80, 0x2c00
	s_addc_u32 s81, s81, 0
	v_pk_fma_f32 v[236:237], v[204:205], v[104:105], v[216:217]
	v_pk_fma_f32 v[236:237], v[208:209], v[96:97], v[236:237]
	v_pk_fma_f32 v[236:237], v[212:213], v[68:69], v[236:237]
	v_pk_fma_f32 v[238:239], v[206:207], v[106:107], v[218:219]
	v_pk_fma_f32 v[238:239], v[210:211], v[98:99], v[238:239]
	v_pk_fma_f32 v[238:239], v[214:215], v[70:71], v[238:239]
	v_pk_mul_f32 v[244:245], v[236:237], v[132:133]
	v_pk_mul_f32 v[246:247], v[238:239], v[132:133]
	v_exp_f32_e32 v244, v244
	v_exp_f32_e32 v245, v245
	v_exp_f32_e32 v246, v246
	v_exp_f32_e32 v247, v247
	v_pk_add_f32 v[244:245], v[244:245], 1.0 op_sel_hi:[1,0]
	v_pk_add_f32 v[246:247], v[246:247], 1.0 op_sel_hi:[1,0]
	v_rcp_f32_e32 v244, v244
	v_rcp_f32_e32 v245, v245
	v_rcp_f32_e32 v246, v246
	v_rcp_f32_e32 v247, v247
	v_pk_mul_f32 v[236:237], v[236:237], v[244:245]
	v_pk_mul_f32 v[238:239], v[238:239], v[246:247]
	v_pk_mul_f32 v[92:93], v[92:93], v[236:237]
	v_pk_mul_f32 v[94:95], v[94:95], v[238:239]
	v_cvt_pk_bf16_f32 v92, v92, v93
	v_cvt_pk_bf16_f32 v93, v94, v95
	global_store_dwordx2 v129, v[92:93], s[80:81] offset:0
	s_add_u32 s80, s80, 0x2c00
	s_addc_u32 s81, s81, 0
	v_pk_fma_f32 v[236:237], v[204:205], v[96:97], v[216:217]
	v_pk_fma_f32 v[236:237], v[208:209], v[68:69], v[236:237]
	v_pk_fma_f32 v[236:237], v[212:213], v[168:169], v[236:237]
	v_pk_fma_f32 v[238:239], v[206:207], v[98:99], v[218:219]
	v_pk_fma_f32 v[238:239], v[210:211], v[70:71], v[238:239]
	v_pk_fma_f32 v[238:239], v[214:215], v[170:171], v[238:239]
	v_pk_mul_f32 v[244:245], v[236:237], v[132:133]
	v_pk_mul_f32 v[246:247], v[238:239], v[132:133]
	v_exp_f32_e32 v244, v244
	v_exp_f32_e32 v245, v245
	v_exp_f32_e32 v246, v246
	v_exp_f32_e32 v247, v247
	v_pk_add_f32 v[244:245], v[244:245], 1.0 op_sel_hi:[1,0]
	v_pk_add_f32 v[246:247], v[246:247], 1.0 op_sel_hi:[1,0]
	v_rcp_f32_e32 v244, v244
	v_rcp_f32_e32 v245, v245
	v_rcp_f32_e32 v246, v246
	v_rcp_f32_e32 v247, v247
	v_pk_mul_f32 v[236:237], v[236:237], v[244:245]
	v_pk_mul_f32 v[238:239], v[238:239], v[246:247]
	v_pk_mul_f32 v[64:65], v[64:65], v[236:237]
	v_pk_mul_f32 v[66:67], v[66:67], v[238:239]
	v_cvt_pk_bf16_f32 v64, v64, v65
	v_cvt_pk_bf16_f32 v65, v66, v67
	s_andn2_b64 exec, exec, s[86:87]
	global_store_dwordx2 v129, v[64:65], s[80:81] offset:0
; DI float silu(float v) { return v * __builtin_amdgcn_rcpf(1.f + __builtin_amdgcn_exp2f(-1.4426950408889634f * v)); }
; DI void st_bf16x4(bf16_t* p, f32x4 v) { u32x2 w; w.x = cvt_pk_bf16(v[0], v[1]); w.y = cvt_pk_bf16(v[2], v[3]); *(u32x2*)p = w; }
;     DI void operator()(const f32x4 (&acc)[2][2][4][2], const Unit& u, int wr, int wc, int fr, int fq) const {
;     ...
; #pragma unroll
;             for (int j = 0; j < 4; ++j) {
;                 float a[8], uu[8];
; #pragma unroll
;                 for (int k = 0; k < 8; ++k) { a[k] = acc[k >> 2][0][k & 3][n][j]; uu[k] = acc[k >> 2][1][k & 3][n][j]; }
;                 const float aprev = __shfl_up(a[7], 1), anext = __shfl_down(a[0], 1);
; #pragma unroll
;                 for (int k = 0; k < 8; ++k) {
;                     const float c = bb[j] + w0[j] * (k > 0 ? a[k - 1] : aprev) + w1[j] * a[k] + w2[j] * (k < 7 ? a[k + 1] : anext);
;                     g[k][j] = silu(c) * uu[k];
;                 }
;                 if (e_lo) { ed_a[j] = a[0]; ed_p[j] = bb[j] + w1[j] * a[0] + w2[j] * a[1]; ed_u[j] = uu[0]; }
;                 if (e_hi) { ed_a[j] = a[7]; ed_p[j] = bb[j] + w0[j] * a[6] + w1[j] * a[7]; ed_u[j] = uu[7]; }
;             }
; #pragma unroll
;             for (int k = 0; k < 8; ++k) {
;                 if ((k == 0 && e_lo) || (k == 7 && e_hi)) continue;
;                 st_bf16x4(G + (row0 + k) * DFF + col, g[k]);
;             }
;             if (e_lo || e_hi) {
;                 const size_t eo = ((size_t)u.pm * 4 + wr * 2 + (e_hi ? 1 : 0)) * DFF + col;
;                 *(f32x4*)(EA + eo) = ed_a; *(f32x4*)(EP + eo) = ed_p; *(f32x4*)(EU + eo) = ed_u;
	s_mov_b64 exec, -1
	v_mov_b32_dpp v164, v4 row_shr:1 row_mask:0xf bank_mask:0xf bound_ctrl:0
	v_mov_b32_dpp v165, v5 row_shr:1 row_mask:0xf bank_mask:0xf bound_ctrl:0
	v_mov_b32_dpp v166, v6 row_shr:1 row_mask:0xf bank_mask:0xf bound_ctrl:0
	v_mov_b32_dpp v167, v7 row_shr:1 row_mask:0xf bank_mask:0xf bound_ctrl:0
	v_mov_b32_dpp v168, v12 row_shl:1 row_mask:0xf bank_mask:0xf bound_ctrl:0
	v_mov_b32_dpp v169, v13 row_shl:1 row_mask:0xf bank_mask:0xf bound_ctrl:0
	v_mov_b32_dpp v170, v14 row_shl:1 row_mask:0xf bank_mask:0xf bound_ctrl:0
	v_mov_b32_dpp v171, v15 row_shl:1 row_mask:0xf bank_mask:0xf bound_ctrl:0
	s_mov_b64 exec, s[84:85]
	v_pk_fma_f32 v[172:173], v[224:225], v[12:13], v[232:233]
	v_pk_fma_f32 v[172:173], v[228:229], v[60:61], v[172:173]
	v_pk_fma_f32 v[174:175], v[226:227], v[14:15], v[234:235]
	v_pk_fma_f32 v[174:175], v[230:231], v[62:63], v[174:175]
	s_add_u32 s82, s50, 0x113a0000
	s_addc_u32 s83, s51, 0
	s_add_u32 s82, s82, s32
	s_addc_u32 s83, s83, 0
	global_store_dwordx4 v130, v[12:15], s[82:83] offset:64
	s_add_u32 s82, s82, 0x318000
	s_addc_u32 s83, s83, 0
	global_store_dwordx4 v130, v[172:175], s[82:83] offset:64
	s_add_u32 s82, s82, 0x318000
	s_addc_u32 s83, s83, 0
	global_store_dwordx4 v130, v[8:11], s[82:83] offset:64
	s_nop 1
	s_mov_b64 exec, s[86:87]
	v_pk_fma_f32 v[172:173], v[220:221], v[20:21], v[232:233]
	v_pk_fma_f32 v[172:173], v[224:225], v[4:5], v[172:173]
	v_pk_fma_f32 v[174:175], v[222:223], v[22:23], v[234:235]
	v_pk_fma_f32 v[174:175], v[226:227], v[6:7], v[174:175]
	s_add_u32 s82, s50, 0x113a0000
	s_addc_u32 s83, s51, 0
	s_add_u32 s82, s82, s32
	s_addc_u32 s83, s83, 0
	global_store_dwordx4 v130, v[4:7], s[82:83] offset:64
	s_add_u32 s82, s82, 0x318000
	s_addc_u32 s83, s83, 0
	global_store_dwordx4 v130, v[172:175], s[82:83] offset:64
	s_add_u32 s82, s82, 0x318000
	s_addc_u32 s83, s83, 0
	global_store_dwordx4 v130, v[0:3], s[82:83] offset:64
	s_nop 1
	s_mov_b64 exec, -1
	s_add_u32 s80, s50, 0x1d9a0000
	s_addc_u32 s81, s51, 0
	s_add_u32 s80, s80, s29
	s_addc_u32 s81, s81, 0
	v_pk_fma_f32 v[236:237], v[220:221], v[164:165], v[232:233]
	v_pk_fma_f32 v[236:237], v[224:225], v[12:13], v[236:237]
	v_pk_fma_f32 v[236:237], v[228:229], v[60:61], v[236:237]
	v_pk_fma_f32 v[238:239], v[222:223], v[166:167], v[234:235]
	v_pk_fma_f32 v[238:239], v[226:227], v[14:15], v[238:239]
	v_pk_fma_f32 v[238:239], v[230:231], v[62:63], v[238:239]
	v_pk_mul_f32 v[244:245], v[236:237], v[132:133]
	v_pk_mul_f32 v[246:247], v[238:239], v[132:133]
	v_exp_f32_e32 v244, v244
	v_exp_f32_e32 v245, v245
	v_exp_f32_e32 v246, v246
	v_exp_f32_e32 v247, v247
	v_pk_add_f32 v[244:245], v[244:245], 1.0 op_sel_hi:[1,0]
	v_pk_add_f32 v[246:247], v[246:247], 1.0 op_sel_hi:[1,0]
	v_rcp_f32_e32 v244, v244
	v_rcp_f32_e32 v245, v245
	v_rcp_f32_e32 v246, v246
	v_rcp_f32_e32 v247, v247
	v_pk_mul_f32 v[236:237], v[236:237], v[244:245]
	v_pk_mul_f32 v[238:239], v[238:239], v[246:247]
	v_pk_mul_f32 v[8:9], v[8:9], v[236:237]
	v_pk_mul_f32 v[10:11], v[10:11], v[238:239]
	v_cvt_pk_bf16_f32 v8, v8, v9
	v_cvt_pk_bf16_f32 v9, v10, v11
	s_andn2_b64 exec, exec, s[84:85]
	global_store_dwordx2 v129, v[8:9], s[80:81] offset:32
	s_mov_b64 exec, -1
	s_add_u32 s80, s80, 0x2c00
	s_addc_u32 s81, s81, 0
	v_pk_fma_f32 v[236:237], v[220:221], v[12:13], v[232:233]
	v_pk_fma_f32 v[236:237], v[224:225], v[60:61], v[236:237]
	v_pk_fma_f32 v[236:237], v[228:229], v[52:53], v[236:237]
	v_pk_fma_f32 v[238:239], v[222:223], v[14:15], v[234:235]
	v_pk_fma_f32 v[238:239], v[226:227], v[62:63], v[238:239]
	v_pk_fma_f32 v[238:239], v[230:231], v[54:55], v[238:239]
	v_pk_mul_f32 v[244:245], v[236:237], v[132:133]
	v_pk_mul_f32 v[246:247], v[238:239], v[132:133]
	v_exp_f32_e32 v244, v244
	v_exp_f32_e32 v245, v245
	v_exp_f32_e32 v246, v246
	v_exp_f32_e32 v247, v247
	v_pk_add_f32 v[244:245], v[244:245], 1.0 op_sel_hi:[1,0]
	v_pk_add_f32 v[246:247], v[246:247], 1.0 op_sel_hi:[1,0]
	v_rcp_f32_e32 v244, v244
	v_rcp_f32_e32 v245, v245
	v_rcp_f32_e32 v246, v246
	v_rcp_f32_e32 v247, v247
	v_pk_mul_f32 v[236:237], v[236:237], v[244:245]
	v_pk_mul_f32 v[238:239], v[238:239], v[246:247]
	v_pk_mul_f32 v[56:57], v[56:57], v[236:237]
	v_pk_mul_f32 v[58:59], v[58:59], v[238:239]
	v_cvt_pk_bf16_f32 v56, v56, v57
	v_cvt_pk_bf16_f32 v57, v58, v59
	global_store_dwordx2 v129, v[56:57], s[80:81] offset:32
	s_add_u32 s80, s80, 0x2c00
	s_addc_u32 s81, s81, 0
	v_pk_fma_f32 v[236:237], v[220:221], v[60:61], v[232:233]
	v_pk_fma_f32 v[236:237], v[224:225], v[52:53], v[236:237]
	v_pk_fma_f32 v[236:237], v[228:229], v[44:45], v[236:237]
	v_pk_fma_f32 v[238:239], v[222:223], v[62:63], v[234:235]
	v_pk_fma_f32 v[238:239], v[226:227], v[54:55], v[238:239]
	v_pk_fma_f32 v[238:239], v[230:231], v[46:47], v[238:239]
	v_pk_mul_f32 v[244:245], v[236:237], v[132:133]
	v_pk_mul_f32 v[246:247], v[238:239], v[132:133]
	v_exp_f32_e32 v244, v244
	v_exp_f32_e32 v245, v245
	v_exp_f32_e32 v246, v246
	v_exp_f32_e32 v247, v247
	v_pk_add_f32 v[244:245], v[244:245], 1.0 op_sel_hi:[1,0]
	v_pk_add_f32 v[246:247], v[246:247], 1.0 op_sel_hi:[1,0]
	v_rcp_f32_e32 v244, v244
	v_rcp_f32_e32 v245, v245
	v_rcp_f32_e32 v246, v246
	v_rcp_f32_e32 v247, v247
	v_pk_mul_f32 v[236:237], v[236:237], v[244:245]
	v_pk_mul_f32 v[238:239], v[238:239], v[246:247]
	v_pk_mul_f32 v[48:49], v[48:49], v[236:237]
	v_pk_mul_f32 v[50:51], v[50:51], v[238:239]
	v_cvt_pk_bf16_f32 v48, v48, v49
	v_cvt_pk_bf16_f32 v49, v50, v51
	global_store_dwordx2 v129, v[48:49], s[80:81] offset:32
	s_add_u32 s80, s80, 0x2c00
	s_addc_u32 s81, s81, 0
	v_pk_fma_f32 v[236:237], v[220:221], v[52:53], v[232:233]
	v_pk_fma_f32 v[236:237], v[224:225], v[44:45], v[236:237]
; DI float silu(float v) { return v * __builtin_amdgcn_rcpf(1.f + __builtin_amdgcn_exp2f(-1.4426950408889634f * v)); }
; DI void st_bf16x4(bf16_t* p, f32x4 v) { u32x2 w; w.x = cvt_pk_bf16(v[0], v[1]); w.y = cvt_pk_bf16(v[2], v[3]); *(u32x2*)p = w; }
;     DI void operator()(const f32x4 (&acc)[2][2][4][2], const Unit& u, int wr, int wc, int fr, int fq) const {
;     ...
; #pragma unroll
;                 for (int k = 0; k < 8; ++k) {
;                     const float c = bb[j] + w0[j] * (k > 0 ? a[k - 1] : aprev) + w1[j] * a[k] + w2[j] * (k < 7 ? a[k + 1] : anext);
;                     g[k][j] = silu(c) * uu[k];
;                 }
;                 if (e_lo) { ed_a[j] = a[0]; ed_p[j] = bb[j] + w1[j] * a[0] + w2[j] * a[1]; ed_u[j] = uu[0]; }
;                 if (e_hi) { ed_a[j] = a[7]; ed_p[j] = bb[j] + w0[j] * a[6] + w1[j] * a[7]; ed_u[j] = uu[7]; }
;             }
; #pragma unroll
;             for (int k = 0; k < 8; ++k) {
;                 if ((k == 0 && e_lo) || (k == 7 && e_hi)) continue;
;                 st_bf16x4(G + (row0 + k) * DFF + col, g[k]);
	v_pk_fma_f32 v[236:237], v[228:229], v[36:37], v[236:237]
	v_pk_fma_f32 v[238:239], v[222:223], v[54:55], v[234:235]
	v_pk_fma_f32 v[238:239], v[226:227], v[46:47], v[238:239]
	v_pk_fma_f32 v[238:239], v[230:231], v[38:39], v[238:239]
	v_pk_mul_f32 v[244:245], v[236:237], v[132:133]
	v_pk_mul_f32 v[246:247], v[238:239], v[132:133]
	v_exp_f32_e32 v244, v244
	v_exp_f32_e32 v245, v245
	v_exp_f32_e32 v246, v246
	v_exp_f32_e32 v247, v247
	v_pk_add_f32 v[244:245], v[244:245], 1.0 op_sel_hi:[1,0]
	v_pk_add_f32 v[246:247], v[246:247], 1.0 op_sel_hi:[1,0]
	v_rcp_f32_e32 v244, v244
	v_rcp_f32_e32 v245, v245
	v_rcp_f32_e32 v246, v246
	v_rcp_f32_e32 v247, v247
	v_pk_mul_f32 v[236:237], v[236:237], v[244:245]
	v_pk_mul_f32 v[238:239], v[238:239], v[246:247]
	v_pk_mul_f32 v[40:41], v[40:41], v[236:237]
	v_pk_mul_f32 v[42:43], v[42:43], v[238:239]
	v_cvt_pk_bf16_f32 v40, v40, v41
	v_cvt_pk_bf16_f32 v41, v42, v43
	global_store_dwordx2 v129, v[40:41], s[80:81] offset:32
	s_add_u32 s80, s80, 0x2c00
	s_addc_u32 s81, s81, 0
	v_pk_fma_f32 v[236:237], v[220:221], v[44:45], v[232:233]
	v_pk_fma_f32 v[236:237], v[224:225], v[36:37], v[236:237]
	v_pk_fma_f32 v[236:237], v[228:229], v[28:29], v[236:237]
	v_pk_fma_f32 v[238:239], v[222:223], v[46:47], v[234:235]
	v_pk_fma_f32 v[238:239], v[226:227], v[38:39], v[238:239]
	v_pk_fma_f32 v[238:239], v[230:231], v[30:31], v[238:239]
	v_pk_mul_f32 v[244:245], v[236:237], v[132:133]
	v_pk_mul_f32 v[246:247], v[238:239], v[132:133]
	v_exp_f32_e32 v244, v244
	v_exp_f32_e32 v245, v245
	v_exp_f32_e32 v246, v246
	v_exp_f32_e32 v247, v247
	v_pk_add_f32 v[244:245], v[244:245], 1.0 op_sel_hi:[1,0]
	v_pk_add_f32 v[246:247], v[246:247], 1.0 op_sel_hi:[1,0]
	v_rcp_f32_e32 v244, v244
	v_rcp_f32_e32 v245, v245
	v_rcp_f32_e32 v246, v246
	v_rcp_f32_e32 v247, v247
	v_pk_mul_f32 v[236:237], v[236:237], v[244:245]
	v_pk_mul_f32 v[238:239], v[238:239], v[246:247]
	v_pk_mul_f32 v[32:33], v[32:33], v[236:237]
	v_pk_mul_f32 v[34:35], v[34:35], v[238:239]
	v_cvt_pk_bf16_f32 v32, v32, v33
	v_cvt_pk_bf16_f32 v33, v34, v35
	global_store_dwordx2 v129, v[32:33], s[80:81] offset:32
	s_add_u32 s80, s80, 0x2c00
	s_addc_u32 s81, s81, 0
	v_pk_fma_f32 v[236:237], v[220:221], v[36:37], v[232:233]
	v_pk_fma_f32 v[236:237], v[224:225], v[28:29], v[236:237]
	v_pk_fma_f32 v[236:237], v[228:229], v[20:21], v[236:237]
	v_pk_fma_f32 v[238:239], v[222:223], v[38:39], v[234:235]
	v_pk_fma_f32 v[238:239], v[226:227], v[30:31], v[238:239]
	v_pk_fma_f32 v[238:239], v[230:231], v[22:23], v[238:239]
	v_pk_mul_f32 v[244:245], v[236:237], v[132:133]
	v_pk_mul_f32 v[246:247], v[238:239], v[132:133]
	v_exp_f32_e32 v244, v244
	v_exp_f32_e32 v245, v245
	v_exp_f32_e32 v246, v246
	v_exp_f32_e32 v247, v247
	v_pk_add_f32 v[244:245], v[244:245], 1.0 op_sel_hi:[1,0]
	v_pk_add_f32 v[246:247], v[246:247], 1.0 op_sel_hi:[1,0]
	v_rcp_f32_e32 v244, v244
	v_rcp_f32_e32 v245, v245
	v_rcp_f32_e32 v246, v246
	v_rcp_f32_e32 v247, v247
	v_pk_mul_f32 v[236:237], v[236:237], v[244:245]
	v_pk_mul_f32 v[238:239], v[238:239], v[246:247]
	v_pk_mul_f32 v[24:25], v[24:25], v[236:237]
	v_pk_mul_f32 v[26:27], v[26:27], v[238:239]
	v_cvt_pk_bf16_f32 v24, v24, v25
	v_cvt_pk_bf16_f32 v25, v26, v27
	global_store_dwordx2 v129, v[24:25], s[80:81] offset:32
	s_add_u32 s80, s80, 0x2c00
	s_addc_u32 s81, s81, 0
	v_pk_fma_f32 v[236:237], v[220:221], v[28:29], v[232:233]
	v_pk_fma_f32 v[236:237], v[224:225], v[20:21], v[236:237]
	v_pk_fma_f32 v[236:237], v[228:229], v[4:5], v[236:237]
	v_pk_fma_f32 v[238:239], v[222:223], v[30:31], v[234:235]
	v_pk_fma_f32 v[238:239], v[226:227], v[22:23], v[238:239]
	v_pk_fma_f32 v[238:239], v[230:231], v[6:7], v[238:239]
	v_pk_mul_f32 v[244:245], v[236:237], v[132:133]
	v_pk_mul_f32 v[246:247], v[238:239], v[132:133]
	v_exp_f32_e32 v244, v244
	v_exp_f32_e32 v245, v245
	v_exp_f32_e32 v246, v246
	v_exp_f32_e32 v247, v247
	v_pk_add_f32 v[244:245], v[244:245], 1.0 op_sel_hi:[1,0]
	v_pk_add_f32 v[246:247], v[246:247], 1.0 op_sel_hi:[1,0]
	v_rcp_f32_e32 v244, v244
	v_rcp_f32_e32 v245, v245
	v_rcp_f32_e32 v246, v246
	v_rcp_f32_e32 v247, v247
	v_pk_mul_f32 v[236:237], v[236:237], v[244:245]
	v_pk_mul_f32 v[238:239], v[238:239], v[246:247]
	v_pk_mul_f32 v[16:17], v[16:17], v[236:237]
	v_pk_mul_f32 v[18:19], v[18:19], v[238:239]
	v_cvt_pk_bf16_f32 v16, v16, v17
	v_cvt_pk_bf16_f32 v17, v18, v19
	global_store_dwordx2 v129, v[16:17], s[80:81] offset:32
	s_add_u32 s80, s80, 0x2c00
	s_addc_u32 s81, s81, 0
	v_pk_fma_f32 v[236:237], v[220:221], v[20:21], v[232:233]
	v_pk_fma_f32 v[236:237], v[224:225], v[4:5], v[236:237]
	v_pk_fma_f32 v[236:237], v[228:229], v[168:169], v[236:237]
	v_pk_fma_f32 v[238:239], v[222:223], v[22:23], v[234:235]
	v_pk_fma_f32 v[238:239], v[226:227], v[6:7], v[238:239]
	v_pk_fma_f32 v[238:239], v[230:231], v[170:171], v[238:239]
	v_pk_mul_f32 v[244:245], v[236:237], v[132:133]
	v_pk_mul_f32 v[246:247], v[238:239], v[132:133]
	v_exp_f32_e32 v244, v244
	v_exp_f32_e32 v245, v245
	v_exp_f32_e32 v246, v246
	v_exp_f32_e32 v247, v247
	v_pk_add_f32 v[244:245], v[244:245], 1.0 op_sel_hi:[1,0]
	v_pk_add_f32 v[246:247], v[246:247], 1.0 op_sel_hi:[1,0]
	v_rcp_f32_e32 v244, v244
	v_rcp_f32_e32 v245, v245
	v_rcp_f32_e32 v246, v246
	v_rcp_f32_e32 v247, v247
	v_pk_mul_f32 v[236:237], v[236:237], v[244:245]
	v_pk_mul_f32 v[238:239], v[238:239], v[246:247]
	v_pk_mul_f32 v[0:1], v[0:1], v[236:237]
	v_pk_mul_f32 v[2:3], v[2:3], v[238:239]
	v_cvt_pk_bf16_f32 v0, v0, v1
	v_cvt_pk_bf16_f32 v1, v2, v3
	s_andn2_b64 exec, exec, s[86:87]
	global_store_dwordx2 v129, v[0:1], s[80:81] offset:32
	s_mov_b64 exec, -1
	s_mov_b64 s[78:79], exec
	s_branch .LBB0_1515

; #define G_STAGE(bufoff, gbase, voff) do { _Pragma("unroll") for (int _i = 0; _i < 2; ++_i) \
;         __builtin_amdgcn_global_load_lds((const unsigned*)((const char*)(gbase) + (voff)[_i]), (LAS unsigned*)(lds + (bufoff) + ldsw + _i * 8192), 16, 0, 0); } while (0)
; #define G_LDA(dst, b, h) do { _Pragma("unroll") for (int m = 0; m < 4; ++m) _Pragma("unroll") for (int k = 0; k < 2; ++k) dst[m][k] = *(const LAS bf16x8*)(lds + G_SA(b, h) + aoff + m * 2048 + k * 1024); } while (0)
; #define G_LDB(dst, b, h) do { _Pragma("unroll") for (int n = 0; n < 2; ++n) _Pragma("unroll") for (int k = 0; k < 2; ++k) dst[n][k] = *(const LAS bf16x8*)(lds + G_SB(b, h) + boff + n * 2048 + k * 1024); } while (0)
; #define G_MMA(ai, bj, At, Bt_) do { __builtin_amdgcn_s_setprio(1); _Pragma("unroll") for (int m = 0; m < 4; ++m) _Pragma("unroll") for (int n = 0; n < 2; ++n) _Pragma("unroll") for (int k = 0; k < 2; ++k) \
;         acc[ai][bj][m][n] = __builtin_amdgcn_mfma_f32_16x16x32_bf16(Bt_[n][k], At[m][k], acc[ai][bj][m][n], 0, 0, 0); __builtin_amdgcn_s_setprio(0); } while (0)
; #define G_WAIT_V(n) asm volatile("s_waitcnt vmcnt(" #n ")" ::: "memory")
; #define G_WAIT_L(n) asm volatile("s_waitcnt lgkmcnt(" #n ")" ::: "memory")
; #define G_BAR __builtin_amdgcn_s_barrier()
; #define G_SCHED __builtin_amdgcn_sched_barrier(0)
; template <class Epi, bool PERMROWS = false>
; DI void gemm_phase(LAS unsigned char* lds, const bf16_t* A, int lda, const bf16_t* Bt, int K, const Sched& S, const Epi& E) {
;     ...
;             G_LDB(B0, 0, 0); G_SCHED; G_LDA(At, 0, 0); G_STAGE(G_SA(1, 1), a1 + hstepA, voffA);
;             G_WAIT_L(8); G_BAR; G_WAIT_L(0); G_MMA(0, 0, At, B0); G_BAR; G_SCHED;
;             G_LDB(B1, 0, 1); G_STAGE(G_SB(0, 0), b2, voffB);
;             G_BAR; G_WAIT_L(0); G_MMA(0, 1, At, B1); G_BAR;
;             G_LDA(At, 0, 1); G_STAGE(G_SA(0, 0), a2, voffA);
;             G_BAR; G_WAIT_L(0); G_MMA(1, 0, At, B0); G_BAR; G_SCHED;
;             G_STAGE(G_SB(0, 1), b2 + hstepB, voffB);
;             G_WAIT_V(6); G_BAR; G_MMA(1, 1, At, B1); G_BAR;
.LBB0_2970:
	ds_read_b128 v[128:131], v183
	ds_read_b128 v[132:135], v183 offset:1024
	ds_read_b128 v[136:139], v183 offset:2048
	ds_read_b128 v[140:143], v183 offset:3072
	s_add_u32 s68, s62, 0x100
	s_addc_u32 s69, s63, 0
	s_cmp_eq_u32 s29, 28
	s_cselect_b32 s73, s43, s69
	s_cselect_b32 s72, s92, s68
	s_cselect_b32 s71, s41, s28
	s_cselect_b32 s70, s93, s94
	v_lshl_add_u64 v[200:201], s[62:63], 0, v[158:159]
	s_add_i32 m0, s54, 0xc000
	ds_read_b128 v[164:167], v184
	ds_read_b128 v[168:171], v184 offset:1024
	ds_read_b128 v[172:175], v184 offset:2048
	ds_read_b128 v[176:179], v184 offset:3072
	ds_read_b128 v[188:191], v184 offset:4096
	ds_read_b128 v[192:195], v184 offset:5120
	ds_read_b128 v[196:199], v184 offset:6144
	ds_read_b128 v[204:207], v184 offset:7168
	global_load_lds_dwordx4 v[200:201], off
	v_lshl_add_u64 v[200:201], s[62:63], 0, v[156:157]
	s_add_i32 m0, s54, 0xe000
	s_nop 0
	global_load_lds_dwordx4 v[200:201], off
	s_waitcnt lgkmcnt(8)
	s_barrier
	s_waitcnt lgkmcnt(0)
	s_setprio 1
	s_waitcnt lgkmcnt(0)
	v_mfma_f32_16x16x32_bf16 v[84:87], v[128:131], v[164:167], v[84:87]
	v_mfma_f32_16x16x32_bf16 v[12:15], v[136:139], v[164:167], v[12:15]
	v_mfma_f32_16x16x32_bf16 v[88:91], v[128:131], v[172:175], v[88:91]
	v_mfma_f32_16x16x32_bf16 v[60:63], v[136:139], v[172:175], v[60:63]
	v_mfma_f32_16x16x32_bf16 v[80:83], v[128:131], v[188:191], v[80:83]
	v_mfma_f32_16x16x32_bf16 v[56:59], v[136:139], v[188:191], v[56:59]
	v_mfma_f32_16x16x32_bf16 v[76:79], v[128:131], v[196:199], v[76:79]
	v_mfma_f32_16x16x32_bf16 v[52:55], v[136:139], v[196:199], v[52:55]
	v_mfma_f32_16x16x32_bf16 v[84:87], v[132:135], v[168:171], v[84:87]
	v_mfma_f32_16x16x32_bf16 v[12:15], v[140:143], v[168:171], v[12:15]
	v_mfma_f32_16x16x32_bf16 v[88:91], v[132:135], v[176:179], v[88:91]
	v_mfma_f32_16x16x32_bf16 v[60:63], v[140:143], v[176:179], v[60:63]
	v_mfma_f32_16x16x32_bf16 v[80:83], v[132:135], v[192:195], v[80:83]
	v_mfma_f32_16x16x32_bf16 v[56:59], v[140:143], v[192:195], v[56:59]
	v_mfma_f32_16x16x32_bf16 v[76:79], v[132:135], v[204:207], v[76:79]
	v_mfma_f32_16x16x32_bf16 v[52:55], v[140:143], v[204:207], v[52:55]
	s_setprio 0
	s_barrier
	s_add_i32 s62, s83, s23
	v_lshl_add_u64 v[200:201], s[70:71], 0, v[148:149]
	s_mov_b32 m0, s62
	ds_read_b128 v[208:211], v185
	ds_read_b128 v[212:215], v185 offset:1024
	ds_read_b128 v[216:219], v185 offset:2048
	ds_read_b128 v[220:223], v185 offset:3072
	global_load_lds_dwordx4 v[200:201], off
	v_lshl_add_u64 v[224:225], s[70:71], 0, v[144:145]
	s_add_i32 m0, s62, 0x2000
	s_nop 0
	global_load_lds_dwordx4 v[224:225], off
	s_barrier
	s_waitcnt lgkmcnt(0)
	s_setprio 1
	s_waitcnt lgkmcnt(0)
	v_mfma_f32_16x16x32_bf16 v[72:75], v[208:211], v[164:167], v[72:75]
	v_mfma_f32_16x16x32_bf16 v[8:11], v[216:219], v[164:167], v[8:11]
	v_mfma_f32_16x16x32_bf16 v[124:127], v[208:211], v[172:175], v[124:127]
	v_mfma_f32_16x16x32_bf16 v[48:51], v[216:219], v[172:175], v[48:51]
	v_mfma_f32_16x16x32_bf16 v[120:123], v[208:211], v[188:191], v[120:123]
	v_mfma_f32_16x16x32_bf16 v[44:47], v[216:219], v[188:191], v[44:47]
	v_mfma_f32_16x16x32_bf16 v[116:119], v[208:211], v[196:199], v[116:119]
	v_mfma_f32_16x16x32_bf16 v[40:43], v[216:219], v[196:199], v[40:43]
	v_mfma_f32_16x16x32_bf16 v[72:75], v[212:215], v[168:171], v[72:75]
	v_mfma_f32_16x16x32_bf16 v[8:11], v[220:223], v[168:171], v[8:11]
	v_mfma_f32_16x16x32_bf16 v[124:127], v[212:215], v[176:179], v[124:127]
	v_mfma_f32_16x16x32_bf16 v[48:51], v[220:223], v[176:179], v[48:51]
	v_mfma_f32_16x16x32_bf16 v[120:123], v[212:215], v[192:195], v[120:123]
	v_mfma_f32_16x16x32_bf16 v[44:47], v[220:223], v[192:195], v[44:47]
	v_mfma_f32_16x16x32_bf16 v[116:119], v[212:215], v[204:207], v[116:119]
	v_mfma_f32_16x16x32_bf16 v[40:43], v[220:223], v[204:207], v[40:43]
	s_setprio 0
	s_mov_b32 m0, s54
	v_lshl_add_u64 v[226:227], s[72:73], 0, v[150:151]
	s_barrier
	ds_read_b128 v[164:167], v184 offset:16384
	ds_read_b128 v[168:171], v184 offset:17408
	ds_read_b128 v[172:175], v184 offset:18432
	ds_read_b128 v[176:179], v184 offset:19456
	ds_read_b128 v[188:191], v184 offset:20480
	ds_read_b128 v[192:195], v184 offset:21504
	ds_read_b128 v[196:199], v184 offset:22528
	ds_read_b128 v[204:207], v184 offset:23552
	global_load_lds_dwordx4 v[226:227], off
	v_lshl_add_u64 v[228:229], s[72:73], 0, v[146:147]
	s_mov_b32 m0, s74
	s_nop 0
	global_load_lds_dwordx4 v[228:229], off
	s_barrier
	s_waitcnt lgkmcnt(0)
	s_setprio 1
	s_waitcnt lgkmcnt(0)
	v_mfma_f32_16x16x32_bf16 v[112:115], v[128:131], v[164:167], v[112:115]
	v_mfma_f32_16x16x32_bf16 v[36:39], v[136:139], v[164:167], v[36:39]
	v_mfma_f32_16x16x32_bf16 v[108:111], v[128:131], v[172:175], v[108:111]
	v_mfma_f32_16x16x32_bf16 v[32:35], v[136:139], v[172:175], v[32:35]
	v_mfma_f32_16x16x32_bf16 v[104:107], v[128:131], v[188:191], v[104:107]
	v_mfma_f32_16x16x32_bf16 v[28:31], v[136:139], v[188:191], v[28:31]
	v_mfma_f32_16x16x32_bf16 v[68:71], v[128:131], v[196:199], v[68:71]
	v_mfma_f32_16x16x32_bf16 v[4:7], v[136:139], v[196:199], v[4:7]
	v_mfma_f32_16x16x32_bf16 v[112:115], v[132:135], v[168:171], v[112:115]
	v_mfma_f32_16x16x32_bf16 v[36:39], v[140:143], v[168:171], v[36:39]
	v_mfma_f32_16x16x32_bf16 v[108:111], v[132:135], v[176:179], v[108:111]
	v_mfma_f32_16x16x32_bf16 v[32:35], v[140:143], v[176:179], v[32:35]
	v_mfma_f32_16x16x32_bf16 v[104:107], v[132:135], v[192:195], v[104:107]
	v_mfma_f32_16x16x32_bf16 v[28:31], v[140:143], v[192:195], v[28:31]
	v_mfma_f32_16x16x32_bf16 v[68:71], v[132:135], v[204:207], v[68:71]
	v_mfma_f32_16x16x32_bf16 v[4:7], v[140:143], v[204:207], v[4:7]
	s_setprio 0
	s_barrier
; #define G_STAGE(bufoff, gbase, voff) do { _Pragma("unroll") for (int _i = 0; _i < 2; ++_i) \
;         __builtin_amdgcn_global_load_lds((const unsigned*)((const char*)(gbase) + (voff)[_i]), (LAS unsigned*)(lds + (bufoff) + ldsw + _i * 8192), 16, 0, 0); } while (0)
; #define G_LDA(dst, b, h) do { _Pragma("unroll") for (int m = 0; m < 4; ++m) _Pragma("unroll") for (int k = 0; k < 2; ++k) dst[m][k] = *(const LAS bf16x8*)(lds + G_SA(b, h) + aoff + m * 2048 + k * 1024); } while (0)
; #define G_LDB(dst, b, h) do { _Pragma("unroll") for (int n = 0; n < 2; ++n) _Pragma("unroll") for (int k = 0; k < 2; ++k) dst[n][k] = *(const LAS bf16x8*)(lds + G_SB(b, h) + boff + n * 2048 + k * 1024); } while (0)
; #define G_MMA(ai, bj, At, Bt_) do { __builtin_amdgcn_s_setprio(1); _Pragma("unroll") for (int m = 0; m < 4; ++m) _Pragma("unroll") for (int n = 0; n < 2; ++n) _Pragma("unroll") for (int k = 0; k < 2; ++k) \
;         acc[ai][bj][m][n] = __builtin_amdgcn_mfma_f32_16x16x32_bf16(Bt_[n][k], At[m][k], acc[ai][bj][m][n], 0, 0, 0); __builtin_amdgcn_s_setprio(0); } while (0)
; #define G_WAIT_V(n) asm volatile("s_waitcnt vmcnt(" #n ")" ::: "memory")
; #define G_WAIT_L(n) asm volatile("s_waitcnt lgkmcnt(" #n ")" ::: "memory")
; #define G_BAR __builtin_amdgcn_s_barrier()
; #define G_SCHED __builtin_amdgcn_sched_barrier(0)
; template <class Epi, bool PERMROWS = false>
; DI void gemm_phase(LAS unsigned char* lds, const bf16_t* A, int lda, const bf16_t* Bt, int K, const Sched& S, const Epi& E) {
;     ...
;             G_WAIT_V(6); G_BAR; G_MMA(1, 1, At, B1); G_BAR;
;             G_LDB(B0, 1, 0); G_SCHED; G_LDA(At, 1, 0); G_STAGE(G_SA(0, 1), a2 + hstepA, voffA);
;             G_WAIT_L(8); G_BAR; G_WAIT_L(0); G_MMA(0, 0, At, B0); G_BAR; G_SCHED;
;             G_LDB(B1, 1, 1); G_STAGE(G_SB(1, 0), b3, voffB);
;             G_BAR; G_WAIT_L(0); G_MMA(0, 1, At, B1); G_BAR;
;             G_LDA(At, 1, 1); G_STAGE(G_SA(1, 0), a3, voffA);
;             G_BAR; G_WAIT_L(0); G_MMA(1, 0, At, B0); G_BAR; G_SCHED;
	s_add_u32 s62, s70, 0x80000
	s_addc_u32 s63, s71, 0
	s_add_i32 s95, s86, s23
	v_lshl_add_u64 v[128:129], s[62:63], 0, v[148:149]
	s_mov_b32 m0, s95
	s_nop 0
	global_load_lds_dwordx4 v[128:129], off
	v_lshl_add_u64 v[128:129], s[62:63], 0, v[144:145]
	s_add_i32 m0, s95, 0x2000
	s_nop 0
	global_load_lds_dwordx4 v[128:129], off
	s_waitcnt vmcnt(6)
	s_barrier
	s_setprio 1
	v_mfma_f32_16x16x32_bf16 v[100:103], v[208:211], v[164:167], v[100:103]
	v_mfma_f32_16x16x32_bf16 v[24:27], v[216:219], v[164:167], v[24:27]
	v_mfma_f32_16x16x32_bf16 v[96:99], v[208:211], v[172:175], v[96:99]
	v_mfma_f32_16x16x32_bf16 v[20:23], v[216:219], v[172:175], v[20:23]
	v_mfma_f32_16x16x32_bf16 v[92:95], v[208:211], v[188:191], v[92:95]
	v_mfma_f32_16x16x32_bf16 v[16:19], v[216:219], v[188:191], v[16:19]
	v_mfma_f32_16x16x32_bf16 v[64:67], v[208:211], v[196:199], v[64:67]
	v_mfma_f32_16x16x32_bf16 v[0:3], v[216:219], v[196:199], v[0:3]
	v_mfma_f32_16x16x32_bf16 v[100:103], v[212:215], v[168:171], v[100:103]
	v_mfma_f32_16x16x32_bf16 v[24:27], v[220:223], v[168:171], v[24:27]
	v_mfma_f32_16x16x32_bf16 v[96:99], v[212:215], v[176:179], v[96:99]
	v_mfma_f32_16x16x32_bf16 v[20:23], v[220:223], v[176:179], v[20:23]
	v_mfma_f32_16x16x32_bf16 v[92:95], v[212:215], v[192:195], v[92:95]
	v_mfma_f32_16x16x32_bf16 v[16:19], v[220:223], v[192:195], v[16:19]
	v_mfma_f32_16x16x32_bf16 v[64:67], v[212:215], v[204:207], v[64:67]
	v_mfma_f32_16x16x32_bf16 v[0:3], v[220:223], v[204:207], v[0:3]
	s_setprio 0
	s_add_i32 s95, 0, 0x18000
	v_add_u32_e32 v140, s95, v181
	s_barrier
	ds_read_b128 v[128:131], v140
	ds_read_b128 v[132:135], v140 offset:1024
	ds_read_b128 v[136:139], v140 offset:2048
	ds_read_b128 v[140:143], v140 offset:3072
	s_add_u32 s62, s72, 0x4000
	s_addc_u32 s63, s73, 0
	s_mov_b32 m0, s75
	v_lshl_add_u64 v[208:209], s[62:63], 0, v[150:151]
	ds_read_b128 v[164:167], v184 offset:32768
	ds_read_b128 v[168:171], v184 offset:33792
	ds_read_b128 v[172:175], v184 offset:34816
	ds_read_b128 v[176:179], v184 offset:35840
	ds_read_b128 v[188:191], v184 offset:36864
	ds_read_b128 v[192:195], v184 offset:37888
	ds_read_b128 v[196:199], v184 offset:38912
	ds_read_b128 v[204:207], v184 offset:39936
	global_load_lds_dwordx4 v[208:209], off
	v_lshl_add_u64 v[208:209], s[62:63], 0, v[146:147]
	s_mov_b32 m0, s76
	s_nop 0
	global_load_lds_dwordx4 v[208:209], off
	s_waitcnt lgkmcnt(8)
	s_barrier
	s_waitcnt lgkmcnt(0)
	s_setprio 1
	s_waitcnt lgkmcnt(0)
	v_mfma_f32_16x16x32_bf16 v[84:87], v[128:131], v[164:167], v[84:87]
	v_mfma_f32_16x16x32_bf16 v[12:15], v[136:139], v[164:167], v[12:15]
	v_mfma_f32_16x16x32_bf16 v[88:91], v[128:131], v[172:175], v[88:91]
	v_mfma_f32_16x16x32_bf16 v[60:63], v[136:139], v[172:175], v[60:63]
	v_mfma_f32_16x16x32_bf16 v[80:83], v[128:131], v[188:191], v[80:83]
	v_mfma_f32_16x16x32_bf16 v[56:59], v[136:139], v[188:191], v[56:59]
	v_mfma_f32_16x16x32_bf16 v[76:79], v[128:131], v[196:199], v[76:79]
	v_mfma_f32_16x16x32_bf16 v[52:55], v[136:139], v[196:199], v[52:55]
	v_mfma_f32_16x16x32_bf16 v[84:87], v[132:135], v[168:171], v[84:87]
	v_mfma_f32_16x16x32_bf16 v[12:15], v[140:143], v[168:171], v[12:15]
	v_mfma_f32_16x16x32_bf16 v[88:91], v[132:135], v[176:179], v[88:91]
	v_mfma_f32_16x16x32_bf16 v[60:63], v[140:143], v[176:179], v[60:63]
	v_mfma_f32_16x16x32_bf16 v[80:83], v[132:135], v[192:195], v[80:83]
	v_mfma_f32_16x16x32_bf16 v[56:59], v[140:143], v[192:195], v[56:59]
	v_mfma_f32_16x16x32_bf16 v[76:79], v[132:135], v[204:207], v[76:79]
	v_mfma_f32_16x16x32_bf16 v[52:55], v[140:143], v[204:207], v[52:55]
	s_setprio 0
	s_barrier
	s_add_i32 s72, 0, 0x1c000
	s_add_i32 s62, s95, s23
	v_add_u32_e32 v187, s72, v181
	v_lshl_add_u64 v[200:201], v[200:201], 0, s[18:19]
	s_mov_b32 m0, s62
	ds_read_b128 v[208:211], v187
	ds_read_b128 v[212:215], v187 offset:1024
	ds_read_b128 v[216:219], v187 offset:2048
	ds_read_b128 v[220:223], v187 offset:3072
	global_load_lds_dwordx4 v[200:201], off
	v_lshl_add_u64 v[200:201], v[224:225], 0, s[18:19]
	s_add_i32 m0, s62, 0x2000
	s_nop 0
	global_load_lds_dwordx4 v[200:201], off
	s_barrier
	s_waitcnt lgkmcnt(0)
	s_setprio 1
	s_waitcnt lgkmcnt(0)
	v_mfma_f32_16x16x32_bf16 v[72:75], v[208:211], v[164:167], v[72:75]
	v_mfma_f32_16x16x32_bf16 v[8:11], v[216:219], v[164:167], v[8:11]
	v_mfma_f32_16x16x32_bf16 v[124:127], v[208:211], v[172:175], v[124:127]
	v_mfma_f32_16x16x32_bf16 v[48:51], v[216:219], v[172:175], v[48:51]
	v_mfma_f32_16x16x32_bf16 v[120:123], v[208:211], v[188:191], v[120:123]
	v_mfma_f32_16x16x32_bf16 v[44:47], v[216:219], v[188:191], v[44:47]
	v_mfma_f32_16x16x32_bf16 v[116:119], v[208:211], v[196:199], v[116:119]
	v_mfma_f32_16x16x32_bf16 v[40:43], v[216:219], v[196:199], v[40:43]
	v_mfma_f32_16x16x32_bf16 v[72:75], v[212:215], v[168:171], v[72:75]
	v_mfma_f32_16x16x32_bf16 v[8:11], v[220:223], v[168:171], v[8:11]
	v_mfma_f32_16x16x32_bf16 v[124:127], v[212:215], v[176:179], v[124:127]
	v_mfma_f32_16x16x32_bf16 v[48:51], v[220:223], v[176:179], v[48:51]
	v_mfma_f32_16x16x32_bf16 v[120:123], v[212:215], v[192:195], v[120:123]
	v_mfma_f32_16x16x32_bf16 v[44:47], v[220:223], v[192:195], v[44:47]
	v_mfma_f32_16x16x32_bf16 v[116:119], v[212:215], v[204:207], v[116:119]
	v_mfma_f32_16x16x32_bf16 v[40:43], v[220:223], v[204:207], v[40:43]
	s_setprio 0
	s_mov_b32 m0, s79
	v_lshl_add_u64 v[200:201], v[226:227], 0, s[18:19]
	s_barrier
	ds_read_b128 v[164:167], v184 offset:49152
	ds_read_b128 v[168:171], v184 offset:50176
	ds_read_b128 v[172:175], v184 offset:51200
	ds_read_b128 v[176:179], v184 offset:52224
	ds_read_b128 v[188:191], v184 offset:53248
	ds_read_b128 v[192:195], v184 offset:54272
	ds_read_b128 v[196:199], v184 offset:55296
	ds_read_b128 v[204:207], v184 offset:56320
	global_load_lds_dwordx4 v[200:201], off
	v_lshl_add_u64 v[200:201], v[228:229], 0, s[18:19]
	s_mov_b32 m0, s81
	s_nop 0
	global_load_lds_dwordx4 v[200:201], off
	s_barrier
; #define G_BAR __builtin_amdgcn_s_barrier()
; template <class Epi, bool PERMROWS = false>
; DI void gemm_phase(LAS unsigned char* lds, const bf16_t* A, int lda, const bf16_t* Bt, int K, const Sched& S, const Epi& E) {
;     ...
;             G_BAR; G_WAIT_L(0); G_MMA(1, 0, At, B0); G_BAR; G_SCHED;
;             G_STAGE(G_SB(1, 1), b3 + hstepB, voffB);
;             G_WAIT_V(6); G_BAR; G_MMA(1, 1, At, B1); G_BAR;
;     DI void operator()(const f32x4 (&acc)[2][2][4][2], const Unit& u, int wr, int wc, int fr, int fq) const {
;         bf16_t* G = (bf16_t*)(ws + WS_G);
;         float* EA = (float*)(ws + WS_EDGE); float* EP = EA + (size_t)36 * 4 * DFF; float* EU = EP + (size_t)36 * 4 * DFF;
;         const int tok0 = (wr * 16 + fr) * 8;
;         const size_t row0 = (size_t)u.pm * BM + tok0;
;         const bool e_lo = (fr == 0), e_hi = (fr == 15);
; #pragma unroll
;         for (int n = 0; n < 2; ++n) {
;             const int col = u.pn * 128 + wc * 32 + n * 16 + 4 * fq;
;             const f32x4 w0 = *(const f32x4*)(cw + col), w1 = *(const f32x4*)(cw + DFF + col), w2 = *(const f32x4*)(cw + 2 * DFF + col), bb = *(const f32x4*)(cb + col);
;             f32x4 g[8];
;             f32x4 ed_a, ed_p, ed_u;
; #pragma unroll
;             for (int j = 0; j < 4; ++j) {
;                 float a[8], uu[8];
; #pragma unroll
;                 for (int k = 0; k < 8; ++k) { a[k] = acc[k >> 2][0][k & 3][n][j]; uu[k] = acc[k >> 2][1][k & 3][n][j]; }
;                 const float aprev = __shfl_up(a[7], 1), anext = __shfl_down(a[0], 1);
; #pragma unroll
;                 for (int k = 0; k < 8; ++k) {
;                     const float c = bb[j] + w0[j] * (k > 0 ? a[k - 1] : aprev) + w1[j] * a[k] + w2[j] * (k < 7 ? a[k + 1] : anext);
;                     g[k][j] = silu(c) * uu[k];
;                 }
;                 if (e_lo) { ed_a[j] = a[0]; ed_p[j] = bb[j] + w1[j] * a[0] + w2[j] * a[1]; ed_u[j] = uu[0]; }
;                 if (e_hi) { ed_a[j] = a[7]; ed_p[j] = bb[j] + w0[j] * a[6] + w1[j] * a[7]; ed_u[j] = uu[7]; }
;             }
; #pragma unroll
;             for (int k = 0; k < 8; ++k) {
;                 if ((k == 0 && e_lo) || (k == 7 && e_hi)) continue;
;                 st_bf16x4(G + (row0 + k) * DFF + col, g[k]);
;             }
;             if (e_lo || e_hi) {
;                 const size_t eo = ((size_t)u.pm * 4 + wr * 2 + (e_hi ? 1 : 0)) * DFF + col;
	s_waitcnt lgkmcnt(0)
	s_setprio 1
	s_waitcnt lgkmcnt(0)
	v_mfma_f32_16x16x32_bf16 v[112:115], v[128:131], v[164:167], v[112:115]
	v_mfma_f32_16x16x32_bf16 v[36:39], v[136:139], v[164:167], v[36:39]
	v_mfma_f32_16x16x32_bf16 v[108:111], v[128:131], v[172:175], v[108:111]
	v_mfma_f32_16x16x32_bf16 v[32:35], v[136:139], v[172:175], v[32:35]
	v_mfma_f32_16x16x32_bf16 v[104:107], v[128:131], v[188:191], v[104:107]
	v_mfma_f32_16x16x32_bf16 v[28:31], v[136:139], v[188:191], v[28:31]
	v_mfma_f32_16x16x32_bf16 v[68:71], v[128:131], v[196:199], v[68:71]
	v_mfma_f32_16x16x32_bf16 v[4:7], v[136:139], v[196:199], v[4:7]
	v_mfma_f32_16x16x32_bf16 v[112:115], v[132:135], v[168:171], v[112:115]
	v_mfma_f32_16x16x32_bf16 v[36:39], v[140:143], v[168:171], v[36:39]
	v_mfma_f32_16x16x32_bf16 v[108:111], v[132:135], v[176:179], v[108:111]
	v_mfma_f32_16x16x32_bf16 v[32:35], v[140:143], v[176:179], v[32:35]
	v_mfma_f32_16x16x32_bf16 v[104:107], v[132:135], v[192:195], v[104:107]
	v_mfma_f32_16x16x32_bf16 v[28:31], v[140:143], v[192:195], v[28:31]
	v_mfma_f32_16x16x32_bf16 v[68:71], v[132:135], v[204:207], v[68:71]
	v_mfma_f32_16x16x32_bf16 v[4:7], v[140:143], v[204:207], v[4:7]
	s_setprio 0
	s_barrier
	s_add_u32 s62, s70, 0x80080
	s_addc_u32 s63, s71, 0
	s_add_i32 s70, s72, s23
	v_lshl_add_u64 v[128:129], s[62:63], 0, v[148:149]
	s_mov_b32 m0, s70
	s_nop 0
	global_load_lds_dwordx4 v[128:129], off
	v_lshl_add_u64 v[128:129], s[62:63], 0, v[144:145]
	s_add_i32 m0, s70, 0x2000
	s_nop 0
	global_load_lds_dwordx4 v[128:129], off
	s_waitcnt vmcnt(6)
	s_barrier
	s_setprio 1
	v_mfma_f32_16x16x32_bf16 v[100:103], v[208:211], v[164:167], v[100:103]
	v_mfma_f32_16x16x32_bf16 v[24:27], v[216:219], v[164:167], v[24:27]
	v_mfma_f32_16x16x32_bf16 v[96:99], v[208:211], v[172:175], v[96:99]
	v_mfma_f32_16x16x32_bf16 v[20:23], v[216:219], v[172:175], v[20:23]
	v_mfma_f32_16x16x32_bf16 v[92:95], v[208:211], v[188:191], v[92:95]
	v_mfma_f32_16x16x32_bf16 v[16:19], v[216:219], v[188:191], v[16:19]
	v_mfma_f32_16x16x32_bf16 v[64:67], v[208:211], v[196:199], v[64:67]
	v_mfma_f32_16x16x32_bf16 v[0:3], v[216:219], v[196:199], v[0:3]
	v_mfma_f32_16x16x32_bf16 v[100:103], v[212:215], v[168:171], v[100:103]
	v_mfma_f32_16x16x32_bf16 v[24:27], v[220:223], v[168:171], v[24:27]
	v_mfma_f32_16x16x32_bf16 v[96:99], v[212:215], v[176:179], v[96:99]
	v_mfma_f32_16x16x32_bf16 v[20:23], v[220:223], v[176:179], v[20:23]
	v_mfma_f32_16x16x32_bf16 v[92:95], v[212:215], v[192:195], v[92:95]
	v_mfma_f32_16x16x32_bf16 v[16:19], v[220:223], v[192:195], v[16:19]
	v_mfma_f32_16x16x32_bf16 v[64:67], v[212:215], v[204:207], v[64:67]
	v_mfma_f32_16x16x32_bf16 v[0:3], v[220:223], v[204:207], v[0:3]
	s_setprio 0
	s_add_i32 s29, s29, 2
	s_add_u32 s94, s94, 0x100
	s_addc_u32 s28, s28, 0
	s_cmp_gt_u32 s29, 29
	s_mov_b64 s[62:63], s[68:69]
	s_barrier
	s_cbranch_scc0 .LBB0_2970
	v_and_b32_e32 v131, 15, v202
	v_bfe_u32 v134, v202, 8, 1
	v_bfe_u32 v135, v202, 6, 2
	v_bfe_u32 v138, v202, 4, 2
	s_lshl_b32 s29, s61, 7
	v_lshlrev_b32_e32 v139, 5, v135
	v_lshl_add_u32 v139, v138, 2, v139
	v_add_u32_e32 v139, s29, v139
	v_lshlrev_b32_e32 v128, 2, v139
	v_lshl_add_u32 v140, v134, 4, v131
	v_mul_u32_u24_e32 v129, 0x16000, v140
	v_lshl_add_u32 v129, v139, 1, v129
	v_cmp_eq_u32_e64 s[70:71], 0, v131
	v_cmp_eq_u32_e64 s[72:73], 15, v131
	v_lshlrev_b32_e32 v130, 1, v134
	v_cndmask_b32_e64 v141, 0, 1, s[72:73]
	v_add_u32_e32 v130, v130, v141
	v_mul_u32_u24_e32 v130, 0x5800, v130
	v_add_u32_e32 v130, v130, v128
	v_mov_b32_e32 v132, 0xbfb8aa3b
	v_mov_b32_e32 v133, 0xbfb8aa3b
	s_mov_b64 s[68:69], s[0:1]
	global_load_dwordx4 v[204:207], v128, s[68:69] offset:0
	global_load_dwordx4 v[220:223], v128, s[68:69] offset:64
	s_add_u32 s68, s68, 0x5800
	s_addc_u32 s69, s69, 0
	global_load_dwordx4 v[208:211], v128, s[68:69] offset:0
	global_load_dwordx4 v[224:227], v128, s[68:69] offset:64
	s_add_u32 s68, s68, 0x5800
	s_addc_u32 s69, s69, 0
	global_load_dwordx4 v[212:215], v128, s[68:69] offset:0
	global_load_dwordx4 v[228:231], v128, s[68:69] offset:64
	global_load_dwordx4 v[216:219], v128, s[16:17] offset:0
	global_load_dwordx4 v[232:235], v128, s[16:17] offset:64
	s_mul_i32 s29, s60, 0x2c0000
	s_mul_i32 s32, s60, 0x16000
	s_waitcnt vmcnt(0)
	v_mov_b32_dpp v164, v68 row_shr:1 row_mask:0xf bank_mask:0xf bound_ctrl:0
	v_mov_b32_dpp v165, v69 row_shr:1 row_mask:0xf bank_mask:0xf bound_ctrl:0
	v_mov_b32_dpp v166, v70 row_shr:1 row_mask:0xf bank_mask:0xf bound_ctrl:0
	v_mov_b32_dpp v167, v71 row_shr:1 row_mask:0xf bank_mask:0xf bound_ctrl:0
	v_mov_b32_dpp v168, v84 row_shl:1 row_mask:0xf bank_mask:0xf bound_ctrl:0
	v_mov_b32_dpp v169, v85 row_shl:1 row_mask:0xf bank_mask:0xf bound_ctrl:0
	v_mov_b32_dpp v170, v86 row_shl:1 row_mask:0xf bank_mask:0xf bound_ctrl:0
	v_mov_b32_dpp v171, v87 row_shl:1 row_mask:0xf bank_mask:0xf bound_ctrl:0
	s_mov_b64 exec, s[70:71]
	v_pk_fma_f32 v[172:173], v[208:209], v[84:85], v[216:217]
	v_pk_fma_f32 v[172:173], v[212:213], v[88:89], v[172:173]
	v_pk_fma_f32 v[174:175], v[210:211], v[86:87], v[218:219]
	v_pk_fma_f32 v[174:175], v[214:215], v[90:91], v[174:175]
	s_add_u32 s68, s50, 0x113a0000
	s_addc_u32 s69, s51, 0
	s_add_u32 s68, s68, s32
	s_addc_u32 s69, s69, 0
	global_store_dwordx4 v130, v[84:87], s[68:69] offset:0
	s_add_u32 s68, s68, 0x318000
	s_addc_u32 s69, s69, 0
	global_store_dwordx4 v130, v[172:175], s[68:69] offset:0
	s_add_u32 s68, s68, 0x318000
	s_addc_u32 s69, s69, 0
	global_store_dwordx4 v130, v[72:75], s[68:69] offset:0
	s_nop 1
	s_mov_b64 exec, s[72:73]
	v_pk_fma_f32 v[172:173], v[204:205], v[104:105], v[216:217]
	v_pk_fma_f32 v[172:173], v[208:209], v[68:69], v[172:173]
; DI float silu(float v) { return v * __builtin_amdgcn_rcpf(1.f + __builtin_amdgcn_exp2f(-1.4426950408889634f * v)); }
; DI void st_bf16x4(bf16_t* p, f32x4 v) { u32x2 w; w.x = cvt_pk_bf16(v[0], v[1]); w.y = cvt_pk_bf16(v[2], v[3]); *(u32x2*)p = w; }
;     DI void operator()(const f32x4 (&acc)[2][2][4][2], const Unit& u, int wr, int wc, int fr, int fq) const {
;     ...
;                 for (int k = 0; k < 8; ++k) { a[k] = acc[k >> 2][0][k & 3][n][j]; uu[k] = acc[k >> 2][1][k & 3][n][j]; }
;                 const float aprev = __shfl_up(a[7], 1), anext = __shfl_down(a[0], 1);
; #pragma unroll
;                 for (int k = 0; k < 8; ++k) {
;                     const float c = bb[j] + w0[j] * (k > 0 ? a[k - 1] : aprev) + w1[j] * a[k] + w2[j] * (k < 7 ? a[k + 1] : anext);
;                     g[k][j] = silu(c) * uu[k];
;                 }
;                 if (e_lo) { ed_a[j] = a[0]; ed_p[j] = bb[j] + w1[j] * a[0] + w2[j] * a[1]; ed_u[j] = uu[0]; }
;                 if (e_hi) { ed_a[j] = a[7]; ed_p[j] = bb[j] + w0[j] * a[6] + w1[j] * a[7]; ed_u[j] = uu[7]; }
;             }
; #pragma unroll
;             for (int k = 0; k < 8; ++k) {
;                 if ((k == 0 && e_lo) || (k == 7 && e_hi)) continue;
;                 st_bf16x4(G + (row0 + k) * DFF + col, g[k]);
;             }
;             if (e_lo || e_hi) {
;                 const size_t eo = ((size_t)u.pm * 4 + wr * 2 + (e_hi ? 1 : 0)) * DFF + col;
;                 *(f32x4*)(EA + eo) = ed_a; *(f32x4*)(EP + eo) = ed_p; *(f32x4*)(EU + eo) = ed_u;
	v_pk_fma_f32 v[174:175], v[206:207], v[106:107], v[218:219]
	v_pk_fma_f32 v[174:175], v[210:211], v[70:71], v[174:175]
	s_add_u32 s68, s50, 0x113a0000
	s_addc_u32 s69, s51, 0
	s_add_u32 s68, s68, s32
	s_addc_u32 s69, s69, 0
	global_store_dwordx4 v130, v[68:71], s[68:69] offset:0
	s_add_u32 s68, s68, 0x318000
	s_addc_u32 s69, s69, 0
	global_store_dwordx4 v130, v[172:175], s[68:69] offset:0
	s_add_u32 s68, s68, 0x318000
	s_addc_u32 s69, s69, 0
	global_store_dwordx4 v130, v[64:67], s[68:69] offset:0
	s_nop 1
	s_mov_b64 exec, -1
	s_add_u32 s62, s50, 0x1d9a0000
	s_addc_u32 s63, s51, 0
	s_add_u32 s62, s62, s29
	s_addc_u32 s63, s63, 0
	v_pk_fma_f32 v[236:237], v[204:205], v[164:165], v[216:217]
	v_pk_fma_f32 v[236:237], v[208:209], v[84:85], v[236:237]
	v_pk_fma_f32 v[236:237], v[212:213], v[88:89], v[236:237]
	v_pk_fma_f32 v[238:239], v[206:207], v[166:167], v[218:219]
	v_pk_fma_f32 v[238:239], v[210:211], v[86:87], v[238:239]
	v_pk_fma_f32 v[238:239], v[214:215], v[90:91], v[238:239]
	v_pk_mul_f32 v[244:245], v[236:237], v[132:133]
	v_pk_mul_f32 v[246:247], v[238:239], v[132:133]
	v_exp_f32_e32 v244, v244
	v_exp_f32_e32 v245, v245
	v_exp_f32_e32 v246, v246
	v_exp_f32_e32 v247, v247
	v_pk_add_f32 v[244:245], v[244:245], 1.0 op_sel_hi:[1,0]
	v_pk_add_f32 v[246:247], v[246:247], 1.0 op_sel_hi:[1,0]
	v_rcp_f32_e32 v244, v244
	v_rcp_f32_e32 v245, v245
	v_rcp_f32_e32 v246, v246
	v_rcp_f32_e32 v247, v247
	v_pk_mul_f32 v[236:237], v[236:237], v[244:245]
	v_pk_mul_f32 v[238:239], v[238:239], v[246:247]
	v_pk_mul_f32 v[72:73], v[72:73], v[236:237]
	v_pk_mul_f32 v[74:75], v[74:75], v[238:239]
	v_cvt_pk_bf16_f32 v72, v72, v73
	v_cvt_pk_bf16_f32 v73, v74, v75
	s_andn2_b64 exec, exec, s[70:71]
	global_store_dwordx2 v129, v[72:73], s[62:63] offset:0
	s_mov_b64 exec, -1
	s_add_u32 s62, s62, 0x2c00
	s_addc_u32 s63, s63, 0
	v_pk_fma_f32 v[236:237], v[204:205], v[84:85], v[216:217]
	v_pk_fma_f32 v[236:237], v[208:209], v[88:89], v[236:237]
	v_pk_fma_f32 v[236:237], v[212:213], v[80:81], v[236:237]
	v_pk_fma_f32 v[238:239], v[206:207], v[86:87], v[218:219]
	v_pk_fma_f32 v[238:239], v[210:211], v[90:91], v[238:239]
	v_pk_fma_f32 v[238:239], v[214:215], v[82:83], v[238:239]
	v_pk_mul_f32 v[244:245], v[236:237], v[132:133]
	v_pk_mul_f32 v[246:247], v[238:239], v[132:133]
	v_exp_f32_e32 v244, v244
	v_exp_f32_e32 v245, v245
	v_exp_f32_e32 v246, v246
	v_exp_f32_e32 v247, v247
	v_pk_add_f32 v[244:245], v[244:245], 1.0 op_sel_hi:[1,0]
	v_pk_add_f32 v[246:247], v[246:247], 1.0 op_sel_hi:[1,0]
	v_rcp_f32_e32 v244, v244
	v_rcp_f32_e32 v245, v245
	v_rcp_f32_e32 v246, v246
	v_rcp_f32_e32 v247, v247
	v_pk_mul_f32 v[236:237], v[236:237], v[244:245]
	v_pk_mul_f32 v[238:239], v[238:239], v[246:247]
	v_pk_mul_f32 v[124:125], v[124:125], v[236:237]
	v_pk_mul_f32 v[126:127], v[126:127], v[238:239]
	v_cvt_pk_bf16_f32 v124, v124, v125
	v_cvt_pk_bf16_f32 v125, v126, v127
	global_store_dwordx2 v129, v[124:125], s[62:63] offset:0
	s_add_u32 s62, s62, 0x2c00
	s_addc_u32 s63, s63, 0
	v_pk_fma_f32 v[236:237], v[204:205], v[88:89], v[216:217]
	v_pk_fma_f32 v[236:237], v[208:209], v[80:81], v[236:237]
	v_pk_fma_f32 v[236:237], v[212:213], v[76:77], v[236:237]
	v_pk_fma_f32 v[238:239], v[206:207], v[90:91], v[218:219]
	v_pk_fma_f32 v[238:239], v[210:211], v[82:83], v[238:239]
	v_pk_fma_f32 v[238:239], v[214:215], v[78:79], v[238:239]
	v_pk_mul_f32 v[244:245], v[236:237], v[132:133]
	v_pk_mul_f32 v[246:247], v[238:239], v[132:133]
	v_exp_f32_e32 v244, v244
	v_exp_f32_e32 v245, v245
	v_exp_f32_e32 v246, v246
	v_exp_f32_e32 v247, v247
	v_pk_add_f32 v[244:245], v[244:245], 1.0 op_sel_hi:[1,0]
	v_pk_add_f32 v[246:247], v[246:247], 1.0 op_sel_hi:[1,0]
	v_rcp_f32_e32 v244, v244
	v_rcp_f32_e32 v245, v245
	v_rcp_f32_e32 v246, v246
	v_rcp_f32_e32 v247, v247
	v_pk_mul_f32 v[236:237], v[236:237], v[244:245]
	v_pk_mul_f32 v[238:239], v[238:239], v[246:247]
	v_pk_mul_f32 v[120:121], v[120:121], v[236:237]
	v_pk_mul_f32 v[122:123], v[122:123], v[238:239]
	v_cvt_pk_bf16_f32 v120, v120, v121
	v_cvt_pk_bf16_f32 v121, v122, v123
	global_store_dwordx2 v129, v[120:121], s[62:63] offset:0
	s_add_u32 s62, s62, 0x2c00
	s_addc_u32 s63, s63, 0
	v_pk_fma_f32 v[236:237], v[204:205], v[80:81], v[216:217]
	v_pk_fma_f32 v[236:237], v[208:209], v[76:77], v[236:237]
	v_pk_fma_f32 v[236:237], v[212:213], v[112:113], v[236:237]
	v_pk_fma_f32 v[238:239], v[206:207], v[82:83], v[218:219]
	v_pk_fma_f32 v[238:239], v[210:211], v[78:79], v[238:239]
	v_pk_fma_f32 v[238:239], v[214:215], v[114:115], v[238:239]
	v_pk_mul_f32 v[244:245], v[236:237], v[132:133]
	v_pk_mul_f32 v[246:247], v[238:239], v[132:133]
	v_exp_f32_e32 v244, v244
	v_exp_f32_e32 v245, v245
	v_exp_f32_e32 v246, v246
	v_exp_f32_e32 v247, v247
	v_pk_add_f32 v[244:245], v[244:245], 1.0 op_sel_hi:[1,0]
	v_pk_add_f32 v[246:247], v[246:247], 1.0 op_sel_hi:[1,0]
	v_rcp_f32_e32 v244, v244
	v_rcp_f32_e32 v245, v245
	v_rcp_f32_e32 v246, v246
	v_rcp_f32_e32 v247, v247
	v_pk_mul_f32 v[236:237], v[236:237], v[244:245]
	v_pk_mul_f32 v[238:239], v[238:239], v[246:247]
	v_pk_mul_f32 v[116:117], v[116:117], v[236:237]
	v_pk_mul_f32 v[118:119], v[118:119], v[238:239]
	v_cvt_pk_bf16_f32 v116, v116, v117
	v_cvt_pk_bf16_f32 v117, v118, v119
	global_store_dwordx2 v129, v[116:117], s[62:63] offset:0
	s_add_u32 s62, s62, 0x2c00
	s_addc_u32 s63, s63, 0
	v_pk_fma_f32 v[236:237], v[204:205], v[76:77], v[216:217]
	v_pk_fma_f32 v[236:237], v[208:209], v[112:113], v[236:237]
	v_pk_fma_f32 v[236:237], v[212:213], v[108:109], v[236:237]
	v_pk_fma_f32 v[238:239], v[206:207], v[78:79], v[218:219]
	v_pk_fma_f32 v[238:239], v[210:211], v[114:115], v[238:239]
	v_pk_fma_f32 v[238:239], v[214:215], v[110:111], v[238:239]
; DI float silu(float v) { return v * __builtin_amdgcn_rcpf(1.f + __builtin_amdgcn_exp2f(-1.4426950408889634f * v)); }
; DI void st_bf16x4(bf16_t* p, f32x4 v) { u32x2 w; w.x = cvt_pk_bf16(v[0], v[1]); w.y = cvt_pk_bf16(v[2], v[3]); *(u32x2*)p = w; }
;     DI void operator()(const f32x4 (&acc)[2][2][4][2], const Unit& u, int wr, int wc, int fr, int fq) const {
;     ...
;                 const float aprev = __shfl_up(a[7], 1), anext = __shfl_down(a[0], 1);
; #pragma unroll
;                 for (int k = 0; k < 8; ++k) {
;                     const float c = bb[j] + w0[j] * (k > 0 ? a[k - 1] : aprev) + w1[j] * a[k] + w2[j] * (k < 7 ? a[k + 1] : anext);
;                     g[k][j] = silu(c) * uu[k];
;                 }
;                 if (e_lo) { ed_a[j] = a[0]; ed_p[j] = bb[j] + w1[j] * a[0] + w2[j] * a[1]; ed_u[j] = uu[0]; }
;                 if (e_hi) { ed_a[j] = a[7]; ed_p[j] = bb[j] + w0[j] * a[6] + w1[j] * a[7]; ed_u[j] = uu[7]; }
;             }
; #pragma unroll
;             for (int k = 0; k < 8; ++k) {
;                 if ((k == 0 && e_lo) || (k == 7 && e_hi)) continue;
;                 st_bf16x4(G + (row0 + k) * DFF + col, g[k]);
;             }
;             if (e_lo || e_hi) {
;                 const size_t eo = ((size_t)u.pm * 4 + wr * 2 + (e_hi ? 1 : 0)) * DFF + col;
;                 *(f32x4*)(EA + eo) = ed_a; *(f32x4*)(EP + eo) = ed_p; *(f32x4*)(EU + eo) = ed_u;
	v_pk_mul_f32 v[244:245], v[236:237], v[132:133]
	v_pk_mul_f32 v[246:247], v[238:239], v[132:133]
	v_exp_f32_e32 v244, v244
	v_exp_f32_e32 v245, v245
	v_exp_f32_e32 v246, v246
	v_exp_f32_e32 v247, v247
	v_pk_add_f32 v[244:245], v[244:245], 1.0 op_sel_hi:[1,0]
	v_pk_add_f32 v[246:247], v[246:247], 1.0 op_sel_hi:[1,0]
	v_rcp_f32_e32 v244, v244
	v_rcp_f32_e32 v245, v245
	v_rcp_f32_e32 v246, v246
	v_rcp_f32_e32 v247, v247
	v_pk_mul_f32 v[236:237], v[236:237], v[244:245]
	v_pk_mul_f32 v[238:239], v[238:239], v[246:247]
	v_pk_mul_f32 v[100:101], v[100:101], v[236:237]
	v_pk_mul_f32 v[102:103], v[102:103], v[238:239]
	v_cvt_pk_bf16_f32 v100, v100, v101
	v_cvt_pk_bf16_f32 v101, v102, v103
	global_store_dwordx2 v129, v[100:101], s[62:63] offset:0
	s_add_u32 s62, s62, 0x2c00
	s_addc_u32 s63, s63, 0
	v_pk_fma_f32 v[236:237], v[204:205], v[112:113], v[216:217]
	v_pk_fma_f32 v[236:237], v[208:209], v[108:109], v[236:237]
	v_pk_fma_f32 v[236:237], v[212:213], v[104:105], v[236:237]
	v_pk_fma_f32 v[238:239], v[206:207], v[114:115], v[218:219]
	v_pk_fma_f32 v[238:239], v[210:211], v[110:111], v[238:239]
	v_pk_fma_f32 v[238:239], v[214:215], v[106:107], v[238:239]
	v_pk_mul_f32 v[244:245], v[236:237], v[132:133]
	v_pk_mul_f32 v[246:247], v[238:239], v[132:133]
	v_exp_f32_e32 v244, v244
	v_exp_f32_e32 v245, v245
	v_exp_f32_e32 v246, v246
	v_exp_f32_e32 v247, v247
	v_pk_add_f32 v[244:245], v[244:245], 1.0 op_sel_hi:[1,0]
	v_pk_add_f32 v[246:247], v[246:247], 1.0 op_sel_hi:[1,0]
	v_rcp_f32_e32 v244, v244
	v_rcp_f32_e32 v245, v245
	v_rcp_f32_e32 v246, v246
	v_rcp_f32_e32 v247, v247
	v_pk_mul_f32 v[236:237], v[236:237], v[244:245]
	v_pk_mul_f32 v[238:239], v[238:239], v[246:247]
	v_pk_mul_f32 v[96:97], v[96:97], v[236:237]
	v_pk_mul_f32 v[98:99], v[98:99], v[238:239]
	v_cvt_pk_bf16_f32 v96, v96, v97
	v_cvt_pk_bf16_f32 v97, v98, v99
	global_store_dwordx2 v129, v[96:97], s[62:63] offset:0
	s_add_u32 s62, s62, 0x2c00
	s_addc_u32 s63, s63, 0
	v_pk_fma_f32 v[236:237], v[204:205], v[108:109], v[216:217]
	v_pk_fma_f32 v[236:237], v[208:209], v[104:105], v[236:237]
	v_pk_fma_f32 v[236:237], v[212:213], v[68:69], v[236:237]
	v_pk_fma_f32 v[238:239], v[206:207], v[110:111], v[218:219]
	v_pk_fma_f32 v[238:239], v[210:211], v[106:107], v[238:239]
	v_pk_fma_f32 v[238:239], v[214:215], v[70:71], v[238:239]
	v_pk_mul_f32 v[244:245], v[236:237], v[132:133]
	v_pk_mul_f32 v[246:247], v[238:239], v[132:133]
	v_exp_f32_e32 v244, v244
	v_exp_f32_e32 v245, v245
	v_exp_f32_e32 v246, v246
	v_exp_f32_e32 v247, v247
	v_pk_add_f32 v[244:245], v[244:245], 1.0 op_sel_hi:[1,0]
	v_pk_add_f32 v[246:247], v[246:247], 1.0 op_sel_hi:[1,0]
	v_rcp_f32_e32 v244, v244
	v_rcp_f32_e32 v245, v245
	v_rcp_f32_e32 v246, v246
	v_rcp_f32_e32 v247, v247
	v_pk_mul_f32 v[236:237], v[236:237], v[244:245]
	v_pk_mul_f32 v[238:239], v[238:239], v[246:247]
	v_pk_mul_f32 v[92:93], v[92:93], v[236:237]
	v_pk_mul_f32 v[94:95], v[94:95], v[238:239]
	v_cvt_pk_bf16_f32 v92, v92, v93
	v_cvt_pk_bf16_f32 v93, v94, v95
	global_store_dwordx2 v129, v[92:93], s[62:63] offset:0
	s_add_u32 s62, s62, 0x2c00
	s_addc_u32 s63, s63, 0
	v_pk_fma_f32 v[236:237], v[204:205], v[104:105], v[216:217]
	v_pk_fma_f32 v[236:237], v[208:209], v[68:69], v[236:237]
	v_pk_fma_f32 v[236:237], v[212:213], v[168:169], v[236:237]
	v_pk_fma_f32 v[238:239], v[206:207], v[106:107], v[218:219]
	v_pk_fma_f32 v[238:239], v[210:211], v[70:71], v[238:239]
	v_pk_fma_f32 v[238:239], v[214:215], v[170:171], v[238:239]
	v_pk_mul_f32 v[244:245], v[236:237], v[132:133]
	v_pk_mul_f32 v[246:247], v[238:239], v[132:133]
	v_exp_f32_e32 v244, v244
	v_exp_f32_e32 v245, v245
	v_exp_f32_e32 v246, v246
	v_exp_f32_e32 v247, v247
	v_pk_add_f32 v[244:245], v[244:245], 1.0 op_sel_hi:[1,0]
	v_pk_add_f32 v[246:247], v[246:247], 1.0 op_sel_hi:[1,0]
	v_rcp_f32_e32 v244, v244
	v_rcp_f32_e32 v245, v245
	v_rcp_f32_e32 v246, v246
	v_rcp_f32_e32 v247, v247
	v_pk_mul_f32 v[236:237], v[236:237], v[244:245]
	v_pk_mul_f32 v[238:239], v[238:239], v[246:247]
	v_pk_mul_f32 v[64:65], v[64:65], v[236:237]
	v_pk_mul_f32 v[66:67], v[66:67], v[238:239]
	v_cvt_pk_bf16_f32 v64, v64, v65
	v_cvt_pk_bf16_f32 v65, v66, v67
	s_andn2_b64 exec, exec, s[72:73]
	global_store_dwordx2 v129, v[64:65], s[62:63] offset:0
	s_mov_b64 exec, -1
	v_mov_b32_dpp v164, v4 row_shr:1 row_mask:0xf bank_mask:0xf bound_ctrl:0
	v_mov_b32_dpp v165, v5 row_shr:1 row_mask:0xf bank_mask:0xf bound_ctrl:0
	v_mov_b32_dpp v166, v6 row_shr:1 row_mask:0xf bank_mask:0xf bound_ctrl:0
	v_mov_b32_dpp v167, v7 row_shr:1 row_mask:0xf bank_mask:0xf bound_ctrl:0
	v_mov_b32_dpp v168, v12 row_shl:1 row_mask:0xf bank_mask:0xf bound_ctrl:0
	v_mov_b32_dpp v169, v13 row_shl:1 row_mask:0xf bank_mask:0xf bound_ctrl:0
	v_mov_b32_dpp v170, v14 row_shl:1 row_mask:0xf bank_mask:0xf bound_ctrl:0
	v_mov_b32_dpp v171, v15 row_shl:1 row_mask:0xf bank_mask:0xf bound_ctrl:0
	s_mov_b64 exec, s[70:71]
	v_pk_fma_f32 v[172:173], v[224:225], v[12:13], v[232:233]
	v_pk_fma_f32 v[172:173], v[228:229], v[60:61], v[172:173]
	v_pk_fma_f32 v[174:175], v[226:227], v[14:15], v[234:235]
	v_pk_fma_f32 v[174:175], v[230:231], v[62:63], v[174:175]
	s_add_u32 s68, s50, 0x113a0000
	s_addc_u32 s69, s51, 0
	s_add_u32 s68, s68, s32
	s_addc_u32 s69, s69, 0
	global_store_dwordx4 v130, v[12:15], s[68:69] offset:64
	s_add_u32 s68, s68, 0x318000
	s_addc_u32 s69, s69, 0
	global_store_dwordx4 v130, v[172:175], s[68:69] offset:64
	s_add_u32 s68, s68, 0x318000
	s_addc_u32 s69, s69, 0
	global_store_dwordx4 v130, v[8:11], s[68:69] offset:64
	s_nop 1
	s_mov_b64 exec, s[72:73]
	v_pk_fma_f32 v[172:173], v[220:221], v[28:29], v[232:233]
	v_pk_fma_f32 v[172:173], v[224:225], v[4:5], v[172:173]
; DI float silu(float v) { return v * __builtin_amdgcn_rcpf(1.f + __builtin_amdgcn_exp2f(-1.4426950408889634f * v)); }
; DI void st_bf16x4(bf16_t* p, f32x4 v) { u32x2 w; w.x = cvt_pk_bf16(v[0], v[1]); w.y = cvt_pk_bf16(v[2], v[3]); *(u32x2*)p = w; }
;     DI void operator()(const f32x4 (&acc)[2][2][4][2], const Unit& u, int wr, int wc, int fr, int fq) const {
;     ...
;                 for (int k = 0; k < 8; ++k) {
;                     const float c = bb[j] + w0[j] * (k > 0 ? a[k - 1] : aprev) + w1[j] * a[k] + w2[j] * (k < 7 ? a[k + 1] : anext);
;                     g[k][j] = silu(c) * uu[k];
;                 }
;                 if (e_lo) { ed_a[j] = a[0]; ed_p[j] = bb[j] + w1[j] * a[0] + w2[j] * a[1]; ed_u[j] = uu[0]; }
;                 if (e_hi) { ed_a[j] = a[7]; ed_p[j] = bb[j] + w0[j] * a[6] + w1[j] * a[7]; ed_u[j] = uu[7]; }
;             }
; #pragma unroll
;             for (int k = 0; k < 8; ++k) {
;                 if ((k == 0 && e_lo) || (k == 7 && e_hi)) continue;
;                 st_bf16x4(G + (row0 + k) * DFF + col, g[k]);
;             }
;             if (e_lo || e_hi) {
;                 const size_t eo = ((size_t)u.pm * 4 + wr * 2 + (e_hi ? 1 : 0)) * DFF + col;
;                 *(f32x4*)(EA + eo) = ed_a; *(f32x4*)(EP + eo) = ed_p; *(f32x4*)(EU + eo) = ed_u;
	v_pk_fma_f32 v[174:175], v[222:223], v[30:31], v[234:235]
	v_pk_fma_f32 v[174:175], v[226:227], v[6:7], v[174:175]
	s_add_u32 s68, s50, 0x113a0000
	s_addc_u32 s69, s51, 0
	s_add_u32 s68, s68, s32
	s_addc_u32 s69, s69, 0
	global_store_dwordx4 v130, v[4:7], s[68:69] offset:64
	s_add_u32 s68, s68, 0x318000
	s_addc_u32 s69, s69, 0
	global_store_dwordx4 v130, v[172:175], s[68:69] offset:64
	s_add_u32 s68, s68, 0x318000
	s_addc_u32 s69, s69, 0
	global_store_dwordx4 v130, v[0:3], s[68:69] offset:64
	s_nop 1
	s_mov_b64 exec, -1
	s_add_u32 s62, s50, 0x1d9a0000
	s_addc_u32 s63, s51, 0
	s_add_u32 s62, s62, s29
	s_addc_u32 s63, s63, 0
	v_pk_fma_f32 v[236:237], v[220:221], v[164:165], v[232:233]
	v_pk_fma_f32 v[236:237], v[224:225], v[12:13], v[236:237]
	v_pk_fma_f32 v[236:237], v[228:229], v[60:61], v[236:237]
	v_pk_fma_f32 v[238:239], v[222:223], v[166:167], v[234:235]
	v_pk_fma_f32 v[238:239], v[226:227], v[14:15], v[238:239]
	v_pk_fma_f32 v[238:239], v[230:231], v[62:63], v[238:239]
	v_pk_mul_f32 v[244:245], v[236:237], v[132:133]
	v_pk_mul_f32 v[246:247], v[238:239], v[132:133]
	v_exp_f32_e32 v244, v244
	v_exp_f32_e32 v245, v245
	v_exp_f32_e32 v246, v246
	v_exp_f32_e32 v247, v247
	v_pk_add_f32 v[244:245], v[244:245], 1.0 op_sel_hi:[1,0]
	v_pk_add_f32 v[246:247], v[246:247], 1.0 op_sel_hi:[1,0]
	v_rcp_f32_e32 v244, v244
	v_rcp_f32_e32 v245, v245
	v_rcp_f32_e32 v246, v246
	v_rcp_f32_e32 v247, v247
	v_pk_mul_f32 v[236:237], v[236:237], v[244:245]
	v_pk_mul_f32 v[238:239], v[238:239], v[246:247]
	v_pk_mul_f32 v[8:9], v[8:9], v[236:237]
	v_pk_mul_f32 v[10:11], v[10:11], v[238:239]
	v_cvt_pk_bf16_f32 v8, v8, v9
	v_cvt_pk_bf16_f32 v9, v10, v11
	s_andn2_b64 exec, exec, s[70:71]
	global_store_dwordx2 v129, v[8:9], s[62:63] offset:32
	s_mov_b64 exec, -1
	s_add_u32 s62, s62, 0x2c00
	s_addc_u32 s63, s63, 0
	v_pk_fma_f32 v[236:237], v[220:221], v[12:13], v[232:233]
	v_pk_fma_f32 v[236:237], v[224:225], v[60:61], v[236:237]
	v_pk_fma_f32 v[236:237], v[228:229], v[56:57], v[236:237]
	v_pk_fma_f32 v[238:239], v[222:223], v[14:15], v[234:235]
	v_pk_fma_f32 v[238:239], v[226:227], v[62:63], v[238:239]
	v_pk_fma_f32 v[238:239], v[230:231], v[58:59], v[238:239]
	v_pk_mul_f32 v[244:245], v[236:237], v[132:133]
	v_pk_mul_f32 v[246:247], v[238:239], v[132:133]
	v_exp_f32_e32 v244, v244
	v_exp_f32_e32 v245, v245
	v_exp_f32_e32 v246, v246
	v_exp_f32_e32 v247, v247
	v_pk_add_f32 v[244:245], v[244:245], 1.0 op_sel_hi:[1,0]
	v_pk_add_f32 v[246:247], v[246:247], 1.0 op_sel_hi:[1,0]
	v_rcp_f32_e32 v244, v244
	v_rcp_f32_e32 v245, v245
	v_rcp_f32_e32 v246, v246
	v_rcp_f32_e32 v247, v247
	v_pk_mul_f32 v[236:237], v[236:237], v[244:245]
	v_pk_mul_f32 v[238:239], v[238:239], v[246:247]
	v_pk_mul_f32 v[48:49], v[48:49], v[236:237]
	v_pk_mul_f32 v[50:51], v[50:51], v[238:239]
	v_cvt_pk_bf16_f32 v48, v48, v49
	v_cvt_pk_bf16_f32 v49, v50, v51
	global_store_dwordx2 v129, v[48:49], s[62:63] offset:32
	s_add_u32 s62, s62, 0x2c00
	s_addc_u32 s63, s63, 0
	v_pk_fma_f32 v[236:237], v[220:221], v[60:61], v[232:233]
	v_pk_fma_f32 v[236:237], v[224:225], v[56:57], v[236:237]
	v_pk_fma_f32 v[236:237], v[228:229], v[52:53], v[236:237]
	v_pk_fma_f32 v[238:239], v[222:223], v[62:63], v[234:235]
	v_pk_fma_f32 v[238:239], v[226:227], v[58:59], v[238:239]
	v_pk_fma_f32 v[238:239], v[230:231], v[54:55], v[238:239]
	v_pk_mul_f32 v[244:245], v[236:237], v[132:133]
	v_pk_mul_f32 v[246:247], v[238:239], v[132:133]
	v_exp_f32_e32 v244, v244
	v_exp_f32_e32 v245, v245
	v_exp_f32_e32 v246, v246
	v_exp_f32_e32 v247, v247
	v_pk_add_f32 v[244:245], v[244:245], 1.0 op_sel_hi:[1,0]
	v_pk_add_f32 v[246:247], v[246:247], 1.0 op_sel_hi:[1,0]
	v_rcp_f32_e32 v244, v244
	v_rcp_f32_e32 v245, v245
	v_rcp_f32_e32 v246, v246
	v_rcp_f32_e32 v247, v247
	v_pk_mul_f32 v[236:237], v[236:237], v[244:245]
	v_pk_mul_f32 v[238:239], v[238:239], v[246:247]
	v_pk_mul_f32 v[44:45], v[44:45], v[236:237]
	v_pk_mul_f32 v[46:47], v[46:47], v[238:239]
	v_cvt_pk_bf16_f32 v44, v44, v45
	v_cvt_pk_bf16_f32 v45, v46, v47
	global_store_dwordx2 v129, v[44:45], s[62:63] offset:32
	s_add_u32 s62, s62, 0x2c00
	s_addc_u32 s63, s63, 0
	v_pk_fma_f32 v[236:237], v[220:221], v[56:57], v[232:233]
	v_pk_fma_f32 v[236:237], v[224:225], v[52:53], v[236:237]
	v_pk_fma_f32 v[236:237], v[228:229], v[36:37], v[236:237]
	v_pk_fma_f32 v[238:239], v[222:223], v[58:59], v[234:235]
	v_pk_fma_f32 v[238:239], v[226:227], v[54:55], v[238:239]
	v_pk_fma_f32 v[238:239], v[230:231], v[38:39], v[238:239]
	v_pk_mul_f32 v[244:245], v[236:237], v[132:133]
	v_pk_mul_f32 v[246:247], v[238:239], v[132:133]
	v_exp_f32_e32 v244, v244
	v_exp_f32_e32 v245, v245
	v_exp_f32_e32 v246, v246
	v_exp_f32_e32 v247, v247
	v_pk_add_f32 v[244:245], v[244:245], 1.0 op_sel_hi:[1,0]
	v_pk_add_f32 v[246:247], v[246:247], 1.0 op_sel_hi:[1,0]
	v_rcp_f32_e32 v244, v244
	v_rcp_f32_e32 v245, v245
	v_rcp_f32_e32 v246, v246
	v_rcp_f32_e32 v247, v247
	v_pk_mul_f32 v[236:237], v[236:237], v[244:245]
; DI float silu(float v) { return v * __builtin_amdgcn_rcpf(1.f + __builtin_amdgcn_exp2f(-1.4426950408889634f * v)); }
; DI void st_bf16x4(bf16_t* p, f32x4 v) { u32x2 w; w.x = cvt_pk_bf16(v[0], v[1]); w.y = cvt_pk_bf16(v[2], v[3]); *(u32x2*)p = w; }
;     DI void operator()(const f32x4 (&acc)[2][2][4][2], const Unit& u, int wr, int wc, int fr, int fq) const {
;     ...
;                 for (int k = 0; k < 8; ++k) {
;                     const float c = bb[j] + w0[j] * (k > 0 ? a[k - 1] : aprev) + w1[j] * a[k] + w2[j] * (k < 7 ? a[k + 1] : anext);
;                     g[k][j] = silu(c) * uu[k];
;                 }
;                 if (e_lo) { ed_a[j] = a[0]; ed_p[j] = bb[j] + w1[j] * a[0] + w2[j] * a[1]; ed_u[j] = uu[0]; }
;                 if (e_hi) { ed_a[j] = a[7]; ed_p[j] = bb[j] + w0[j] * a[6] + w1[j] * a[7]; ed_u[j] = uu[7]; }
;             }
; #pragma unroll
;             for (int k = 0; k < 8; ++k) {
;                 if ((k == 0 && e_lo) || (k == 7 && e_hi)) continue;
;                 st_bf16x4(G + (row0 + k) * DFF + col, g[k]);
	v_pk_mul_f32 v[238:239], v[238:239], v[246:247]
	v_pk_mul_f32 v[40:41], v[40:41], v[236:237]
	v_pk_mul_f32 v[42:43], v[42:43], v[238:239]
	v_cvt_pk_bf16_f32 v40, v40, v41
	v_cvt_pk_bf16_f32 v41, v42, v43
	global_store_dwordx2 v129, v[40:41], s[62:63] offset:32
	s_add_u32 s62, s62, 0x2c00
	s_addc_u32 s63, s63, 0
	v_pk_fma_f32 v[236:237], v[220:221], v[52:53], v[232:233]
	v_pk_fma_f32 v[236:237], v[224:225], v[36:37], v[236:237]
	v_pk_fma_f32 v[236:237], v[228:229], v[32:33], v[236:237]
	v_pk_fma_f32 v[238:239], v[222:223], v[54:55], v[234:235]
	v_pk_fma_f32 v[238:239], v[226:227], v[38:39], v[238:239]
	v_pk_fma_f32 v[238:239], v[230:231], v[34:35], v[238:239]
	v_pk_mul_f32 v[244:245], v[236:237], v[132:133]
	v_pk_mul_f32 v[246:247], v[238:239], v[132:133]
	v_exp_f32_e32 v244, v244
	v_exp_f32_e32 v245, v245
	v_exp_f32_e32 v246, v246
	v_exp_f32_e32 v247, v247
	v_pk_add_f32 v[244:245], v[244:245], 1.0 op_sel_hi:[1,0]
	v_pk_add_f32 v[246:247], v[246:247], 1.0 op_sel_hi:[1,0]
	v_rcp_f32_e32 v244, v244
	v_rcp_f32_e32 v245, v245
	v_rcp_f32_e32 v246, v246
	v_rcp_f32_e32 v247, v247
	v_pk_mul_f32 v[236:237], v[236:237], v[244:245]
	v_pk_mul_f32 v[238:239], v[238:239], v[246:247]
	v_pk_mul_f32 v[24:25], v[24:25], v[236:237]
	v_pk_mul_f32 v[26:27], v[26:27], v[238:239]
	v_cvt_pk_bf16_f32 v24, v24, v25
	v_cvt_pk_bf16_f32 v25, v26, v27
	global_store_dwordx2 v129, v[24:25], s[62:63] offset:32
	s_add_u32 s62, s62, 0x2c00
	s_addc_u32 s63, s63, 0
	v_pk_fma_f32 v[236:237], v[220:221], v[36:37], v[232:233]
	v_pk_fma_f32 v[236:237], v[224:225], v[32:33], v[236:237]
	v_pk_fma_f32 v[236:237], v[228:229], v[28:29], v[236:237]
	v_pk_fma_f32 v[238:239], v[222:223], v[38:39], v[234:235]
	v_pk_fma_f32 v[238:239], v[226:227], v[34:35], v[238:239]
	v_pk_fma_f32 v[238:239], v[230:231], v[30:31], v[238:239]
	v_pk_mul_f32 v[244:245], v[236:237], v[132:133]
	v_pk_mul_f32 v[246:247], v[238:239], v[132:133]
	v_exp_f32_e32 v244, v244
	v_exp_f32_e32 v245, v245
	v_exp_f32_e32 v246, v246
	v_exp_f32_e32 v247, v247
	v_pk_add_f32 v[244:245], v[244:245], 1.0 op_sel_hi:[1,0]
	v_pk_add_f32 v[246:247], v[246:247], 1.0 op_sel_hi:[1,0]
	v_rcp_f32_e32 v244, v244
	v_rcp_f32_e32 v245, v245
	v_rcp_f32_e32 v246, v246
	v_rcp_f32_e32 v247, v247
	v_pk_mul_f32 v[236:237], v[236:237], v[244:245]
	v_pk_mul_f32 v[238:239], v[238:239], v[246:247]
	v_pk_mul_f32 v[20:21], v[20:21], v[236:237]
	v_pk_mul_f32 v[22:23], v[22:23], v[238:239]
	v_cvt_pk_bf16_f32 v20, v20, v21
	v_cvt_pk_bf16_f32 v21, v22, v23
	global_store_dwordx2 v129, v[20:21], s[62:63] offset:32
	s_add_u32 s62, s62, 0x2c00
	s_addc_u32 s63, s63, 0
	v_pk_fma_f32 v[236:237], v[220:221], v[32:33], v[232:233]
	v_pk_fma_f32 v[236:237], v[224:225], v[28:29], v[236:237]
	v_pk_fma_f32 v[236:237], v[228:229], v[4:5], v[236:237]
	v_pk_fma_f32 v[238:239], v[222:223], v[34:35], v[234:235]
	v_pk_fma_f32 v[238:239], v[226:227], v[30:31], v[238:239]
	v_pk_fma_f32 v[238:239], v[230:231], v[6:7], v[238:239]
	v_pk_mul_f32 v[244:245], v[236:237], v[132:133]
	v_pk_mul_f32 v[246:247], v[238:239], v[132:133]
	v_exp_f32_e32 v244, v244
	v_exp_f32_e32 v245, v245
	v_exp_f32_e32 v246, v246
	v_exp_f32_e32 v247, v247
	v_pk_add_f32 v[244:245], v[244:245], 1.0 op_sel_hi:[1,0]
	v_pk_add_f32 v[246:247], v[246:247], 1.0 op_sel_hi:[1,0]
	v_rcp_f32_e32 v244, v244
	v_rcp_f32_e32 v245, v245
	v_rcp_f32_e32 v246, v246
	v_rcp_f32_e32 v247, v247
	v_pk_mul_f32 v[236:237], v[236:237], v[244:245]
	v_pk_mul_f32 v[238:239], v[238:239], v[246:247]
	v_pk_mul_f32 v[16:17], v[16:17], v[236:237]
	v_pk_mul_f32 v[18:19], v[18:19], v[238:239]
	v_cvt_pk_bf16_f32 v16, v16, v17
	v_cvt_pk_bf16_f32 v17, v18, v19
	global_store_dwordx2 v129, v[16:17], s[62:63] offset:32
	s_add_u32 s62, s62, 0x2c00
	s_addc_u32 s63, s63, 0
	v_pk_fma_f32 v[236:237], v[220:221], v[28:29], v[232:233]
	v_pk_fma_f32 v[236:237], v[224:225], v[4:5], v[236:237]
	v_pk_fma_f32 v[236:237], v[228:229], v[168:169], v[236:237]
	v_pk_fma_f32 v[238:239], v[222:223], v[30:31], v[234:235]
	v_pk_fma_f32 v[238:239], v[226:227], v[6:7], v[238:239]
	v_pk_fma_f32 v[238:239], v[230:231], v[170:171], v[238:239]
	v_pk_mul_f32 v[244:245], v[236:237], v[132:133]
	v_pk_mul_f32 v[246:247], v[238:239], v[132:133]
	v_exp_f32_e32 v244, v244
	v_exp_f32_e32 v245, v245
	v_exp_f32_e32 v246, v246
	v_exp_f32_e32 v247, v247
	v_pk_add_f32 v[244:245], v[244:245], 1.0 op_sel_hi:[1,0]
	v_pk_add_f32 v[246:247], v[246:247], 1.0 op_sel_hi:[1,0]
	v_rcp_f32_e32 v244, v244
	v_rcp_f32_e32 v245, v245
	v_rcp_f32_e32 v246, v246
	v_rcp_f32_e32 v247, v247
	v_pk_mul_f32 v[236:237], v[236:237], v[244:245]
	v_pk_mul_f32 v[238:239], v[238:239], v[246:247]
	v_pk_mul_f32 v[0:1], v[0:1], v[236:237]
	v_pk_mul_f32 v[2:3], v[2:3], v[238:239]
	v_cvt_pk_bf16_f32 v0, v0, v1
	v_cvt_pk_bf16_f32 v1, v2, v3
	s_andn2_b64 exec, exec, s[72:73]
	global_store_dwordx2 v129, v[0:1], s[62:63] offset:32
	s_mov_b64 exec, -1
	s_mov_b64 s[60:61], exec
	s_branch .LBB0_2966
